# P5 epilogue loads hoisted; EpiLn (P7,P10): residual rows of 5-6 blocks prefetched in one batch, redundant wbl2/inv around the sc1 stats exchange removed
# speedup vs baseline: 1.0097x; 1.0092x over previous
; #define PG8_LAS __attribute__((address_space(3)))
;     __device__ __forceinline__ void fused(f32x4 (&acc)[2][2][4][2], const Unit& u, int wr, int wc, int fr, int fq, PG8_LAS unsigned char* lds, int wid, int lane) const {
;     ...
; #pragma unroll
;         for (int ai = 0; ai < 2; ++ai)
; #pragma unroll
;             for (int m = 0; m < 4; ++m) {
;                 const int rl = ai * 128 + wr * 64 + m * 16 + fr;
;                 const size_t roff = (size_t)(u.pm * 256 + rl) * 1024 + u.pn * 256 + wc * 32 + fq * 8;
;                 float s1 = 0.f, s2 = 0.f;
; #pragma unroll
;                 for (int bj = 0; bj < 2; ++bj) {
;                     float x[8];
;                     if (RES_BF16) ld8f((const bfu*)res + roff + bj * 128, x);
;                     else ld8f32((const float*)res + roff + bj * 128, x);
; #pragma unroll
;                     for (int n = 0; n < 2; ++n) {
;                         f32x4 v = acc[ai][bj][m][n];
;                         v[0] += ALPHA * x[4 * n]; v[1] += ALPHA * x[4 * n + 1]; v[2] += ALPHA * x[4 * n + 2]; v[3] += ALPHA * x[4 * n + 3];
;                         acc[ai][bj][m][n] = v;
;                         s1 += (v[0] + v[1]) + (v[2] + v[3]); s2 += (v[0] * v[0] + v[1] * v[1]) + (v[2] * v[2] + v[3] * v[3]);
;                     }
;                 }
;                 s1 += __shfl_xor(s1, 16); s1 += __shfl_xor(s1, 32); s2 += __shfl_xor(s2, 16); s2 += __shfl_xor(s2, 32);
;                 {
;                     PG8_LAS float* pd = (fq == 0) ? P + (rl * 4 + wc) * 2 : (PG8_LAS float*)(lds + 12288) + tid * 2;
;                     pd[0] = s1; pd[1] = s2;
;                 }
;             }
.LBB0_1048:
	s_add_u32 s22, s66, 0x38b00000
	s_addc_u32 s23, s67, 0
	s_lshl_b32 s19, s18, 8
	v_add_u32_e32 v142, s19, v129
	s_lshl_b32 s8, s20, 8
	v_ashrrev_i32_e32 v143, 31, v142
	v_readlane_b32 s28, v252, 8
	s_ashr_i32 s9, s8, 31
	v_lshlrev_b64 v[142:143], 11, v[142:143]
	v_readlane_b32 s29, v252, 9
	s_lshl_b64 s[26:27], s[8:9], 1
	s_mov_b32 s25, 0
	v_lshl_add_u64 v[144:145], s[28:29], 0, v[142:143]
	v_lshl_add_u64 v[144:145], v[144:145], 0, s[26:27]
	s_lshl_b32 s24, s11, 6
	v_lshl_add_u64 v[144:145], v[144:145], 0, s[24:25]
	v_mov_b32_e32 v141, 0
	v_lshl_add_u64 v[144:145], v[144:145], 0, v[140:141]
	s_barrier
	global_load_dwordx4 v[146:149], v[144:145], off
	global_load_dwordx4 v[150:153], v[144:145], off offset:256
	s_mov_b64 s[98:99], 0x8000
	v_lshl_add_u64 v[250:251], v[144:145], 0, s[98:99]
	global_load_dwordx4 v[210:213], v[250:251], off
	global_load_dwordx4 v[214:217], v[250:251], off offset:256
	s_mov_b64 s[98:99], 0x10000
	v_lshl_add_u64 v[250:251], v[144:145], 0, s[98:99]
	global_load_dwordx4 v[218:221], v[250:251], off
	global_load_dwordx4 v[222:225], v[250:251], off offset:256
	s_mov_b64 s[98:99], 0x18000
	v_lshl_add_u64 v[250:251], v[144:145], 0, s[98:99]
	global_load_dwordx4 v[226:229], v[250:251], off
	global_load_dwordx4 v[230:233], v[250:251], off offset:256
	s_mov_b64 s[98:99], 0x40000
	v_lshl_add_u64 v[250:251], v[144:145], 0, s[98:99]
	global_load_dwordx4 v[234:237], v[250:251], off
	global_load_dwordx4 v[238:241], v[250:251], off offset:256
	s_mov_b64 s[98:99], 0x48000
	v_lshl_add_u64 v[250:251], v[144:145], 0, s[98:99]
	global_load_dwordx4 v[242:245], v[250:251], off
	global_load_dwordx4 v[246:249], v[250:251], off offset:256
	v_mbcnt_lo_u32_b32 v144, -1, 0
	v_mbcnt_hi_u32_b32 v154, -1, v144
	v_and_b32_e32 v145, 64, v154
	v_or_b32_e32 v178, 16, v129
	v_xor_b32_e32 v155, 16, v154
	v_add_u32_e32 v157, 64, v145
	v_xor_b32_e32 v156, 32, v154
	v_add_u32_e32 v144, s19, v178
	v_cmp_lt_i32_e32 vcc, v155, v157
	v_ashrrev_i32_e32 v145, 31, v144
	v_lshlrev_b64 v[144:145], 11, v[144:145]
	v_cndmask_b32_e32 v155, v154, v155, vcc
	v_cmp_lt_i32_e32 vcc, v156, v157
	v_lshlrev_b32_e32 v181, 2, v155
	s_mov_b32 s6, 0x3f9837f0
	v_cndmask_b32_e32 v154, v154, v156, vcc
	v_lshlrev_b32_e32 v180, 2, v154
	v_lshl_add_u64 v[154:155], s[28:29], 0, v[144:145]
	v_lshl_add_u64 v[154:155], v[154:155], 0, s[26:27]
	v_lshl_add_u64 v[154:155], v[154:155], 0, s[24:25]
	v_lshl_add_u64 v[158:159], v[154:155], 0, v[140:141]
	s_waitcnt vmcnt(0)
	v_mov_b64_e32 v[154:155], v[210:211]
	v_mov_b64_e32 v[156:157], v[212:213]
	s_nop 0
	v_mov_b64_e32 v[158:159], v[214:215]
	v_mov_b64_e32 v[160:161], v[216:217]
	v_or_b32_e32 v179, 32, v129
	v_lshl_add_u32 v177, v172, 3, 0
	v_cmp_eq_u32_e32 vcc, 0, v176
	s_waitcnt vmcnt(0)
	v_lshlrev_b32_e32 v162, 16, v146
	v_and_b32_e32 v163, 0xffff0000, v146
	v_lshlrev_b32_e32 v164, 16, v147
	v_and_b32_e32 v165, 0xffff0000, v147
	v_lshlrev_b32_e32 v166, 16, v148
	v_and_b32_e32 v167, 0xffff0000, v148
	v_lshlrev_b32_e32 v148, 16, v149
	v_and_b32_e32 v149, 0xffff0000, v149
	v_lshlrev_b32_e32 v168, 16, v150
	v_and_b32_e32 v169, 0xffff0000, v150
	v_lshlrev_b32_e32 v150, 16, v151
	v_and_b32_e32 v151, 0xffff0000, v151
	v_lshlrev_b32_e32 v170, 16, v152
	v_and_b32_e32 v171, 0xffff0000, v152
	v_lshlrev_b32_e32 v152, 16, v153
	v_and_b32_e32 v153, 0xffff0000, v153
	v_pk_fma_f32 v[146:147], v[162:163], s[6:7], v[124:125] op_sel_hi:[1,0,1]
	v_pk_fma_f32 v[124:125], v[164:165], s[6:7], v[126:127] op_sel_hi:[1,0,1]
	v_pk_fma_f32 v[126:127], v[166:167], s[6:7], v[120:121] op_sel_hi:[1,0,1]
	v_pk_fma_f32 v[122:123], v[148:149], s[6:7], v[122:123] op_sel_hi:[1,0,1]
	v_pk_fma_f32 v[120:121], v[168:169], s[6:7], v[116:117] op_sel_hi:[1,0,1]
	v_pk_fma_f32 v[116:117], v[150:151], s[6:7], v[118:119] op_sel_hi:[1,0,1]
	v_pk_fma_f32 v[118:119], v[170:171], s[6:7], v[112:113] op_sel_hi:[1,0,1]
	v_pk_fma_f32 v[112:113], v[152:153], s[6:7], v[114:115] op_sel_hi:[1,0,1]
	v_pk_add_f32 v[114:115], v[146:147], v[146:147] op_sel:[0,1] op_sel_hi:[1,0]
	v_pk_add_f32 v[148:149], v[124:125], v[124:125] op_sel:[0,1] op_sel_hi:[1,0]
	v_pk_mul_f32 v[150:151], v[146:147], v[146:147]
	v_pk_mul_f32 v[152:153], v[124:125], v[124:125]
	v_pk_mul_f32 v[162:163], v[126:127], v[126:127]
	v_mul_f32_e32 v164, v122, v122
	v_mov_b32_e32 v182, v126
	v_mov_b32_e32 v184, v122
	v_pk_fma_f32 v[164:165], v[122:123], v[122:123], v[164:165] op_sel_hi:[1,1,0]
	v_mov_b32_e32 v183, v150
	v_mov_b32_e32 v150, v127
	v_mov_b32_e32 v185, v152
	v_mov_b32_e32 v152, v123
	v_mov_b32_e32 v115, v162
	v_mov_b32_e32 v149, v163
	v_pk_add_f32 v[150:151], v[182:183], v[150:151]
	v_pk_add_f32 v[152:153], v[184:185], v[152:153]
	v_pk_add_f32 v[114:115], v[114:115], v[148:149]
	v_mov_b32_e32 v164, v141
	v_pk_mul_f32 v[166:167], v[120:121], v[120:121]
	v_pk_mul_f32 v[168:169], v[116:117], v[116:117]
	v_pk_add_f32 v[150:151], v[150:151], v[152:153]
	v_pk_add_f32 v[114:115], v[114:115], v[164:165]
	v_mov_b32_e32 v188, v120
	v_mov_b32_e32 v189, v166
	v_mov_b32_e32 v166, v121
	v_pk_add_f32 v[114:115], v[150:151], v[114:115]
	v_mov_b32_e32 v150, v116
	v_mov_b32_e32 v151, v168
	v_mov_b32_e32 v168, v117
	v_pk_add_f32 v[148:149], v[188:189], v[166:167]
	v_pk_add_f32 v[150:151], v[150:151], v[168:169]
	v_pk_mul_f32 v[170:171], v[118:119], v[118:119]
	v_pk_mul_f32 v[174:175], v[112:113], v[112:113]
	v_pk_add_f32 v[148:149], v[148:149], v[150:151]
	v_mov_b32_e32 v150, v112
	v_pk_add_f32 v[114:115], v[114:115], v[148:149]
	v_mov_b32_e32 v148, v118
	v_mov_b32_e32 v149, v170
	v_mov_b32_e32 v170, v119
	v_mov_b32_e32 v151, v174
	v_mov_b32_e32 v174, v113
	v_pk_add_f32 v[148:149], v[148:149], v[170:171]
	v_pk_add_f32 v[150:151], v[150:151], v[174:175]
	s_lshl_b32 s7, s11, 3
	v_pk_add_f32 v[148:149], v[148:149], v[150:151]
	s_add_i32 s7, s7, 0
	v_pk_add_f32 v[114:115], v[114:115], v[148:149]
	ds_bpermute_b32 v148, v181, v114
	ds_bpermute_b32 v149, v181, v115
	v_lshlrev_b32_e32 v168, 16, v156
	v_and_b32_e32 v169, 0xffff0000, v156
	v_lshlrev_b32_e32 v156, 16, v157
	v_and_b32_e32 v157, 0xffff0000, v157
	s_waitcnt lgkmcnt(0)
; #define PG8_LAS __attribute__((address_space(3)))
;     __device__ __forceinline__ void fused(f32x4 (&acc)[2][2][4][2], const Unit& u, int wr, int wc, int fr, int fq, PG8_LAS unsigned char* lds, int wid, int lane) const {
;     ...
; #pragma unroll
;         for (int ai = 0; ai < 2; ++ai)
; #pragma unroll
;             for (int m = 0; m < 4; ++m) {
;                 const int rl = ai * 128 + wr * 64 + m * 16 + fr;
;                 const size_t roff = (size_t)(u.pm * 256 + rl) * 1024 + u.pn * 256 + wc * 32 + fq * 8;
;                 float s1 = 0.f, s2 = 0.f;
; #pragma unroll
;                 for (int bj = 0; bj < 2; ++bj) {
;                     float x[8];
;                     if (RES_BF16) ld8f((const bfu*)res + roff + bj * 128, x);
;                     else ld8f32((const float*)res + roff + bj * 128, x);
; #pragma unroll
;                     for (int n = 0; n < 2; ++n) {
;                         f32x4 v = acc[ai][bj][m][n];
;                         v[0] += ALPHA * x[4 * n]; v[1] += ALPHA * x[4 * n + 1]; v[2] += ALPHA * x[4 * n + 2]; v[3] += ALPHA * x[4 * n + 3];
;                         acc[ai][bj][m][n] = v;
;                         s1 += (v[0] + v[1]) + (v[2] + v[3]); s2 += (v[0] * v[0] + v[1] * v[1]) + (v[2] * v[2] + v[3] * v[3]);
;                     }
;                 }
;                 s1 += __shfl_xor(s1, 16); s1 += __shfl_xor(s1, 32); s2 += __shfl_xor(s2, 16); s2 += __shfl_xor(s2, 32);
;                 {
;                     PG8_LAS float* pd = (fq == 0) ? P + (rl * 4 + wc) * 2 : (PG8_LAS float*)(lds + 12288) + tid * 2;
;                     pd[0] = s1; pd[1] = s2;
;                 }
;             }
	v_pk_add_f32 v[162:163], v[114:115], v[148:149]
	v_add_u32_e32 v148, s19, v179
	v_ashrrev_i32_e32 v149, 31, v148
	v_lshlrev_b64 v[148:149], 11, v[148:149]
	v_lshl_add_u64 v[150:151], s[28:29], 0, v[148:149]
	v_lshl_add_u64 v[150:151], v[150:151], 0, s[26:27]
	v_lshl_add_u64 v[150:151], v[150:151], 0, s[24:25]
	v_lshl_add_u64 v[166:167], v[150:151], 0, v[140:141]
	v_mov_b64_e32 v[150:151], v[218:219]
	v_mov_b64_e32 v[152:153], v[220:221]
	v_lshlrev_b32_e32 v114, 16, v154
	v_and_b32_e32 v115, 0xffff0000, v154
	v_lshlrev_b32_e32 v154, 16, v155
	v_and_b32_e32 v155, 0xffff0000, v155
	v_pk_fma_f32 v[114:115], v[114:115], s[6:7], v[108:109] op_sel_hi:[1,0,1]
	v_pk_fma_f32 v[108:109], v[154:155], s[6:7], v[110:111] op_sel_hi:[1,0,1]
	v_pk_fma_f32 v[106:107], v[156:157], s[6:7], v[106:107] op_sel_hi:[1,0,1]
	v_mov_b64_e32 v[154:155], v[222:223]
	v_mov_b64_e32 v[156:157], v[224:225]
	v_pk_fma_f32 v[110:111], v[168:169], s[6:7], v[104:105] op_sel_hi:[1,0,1]
	v_mul_f32_e32 v104, v106, v106
	v_pk_fma_f32 v[190:191], v[106:107], v[106:107], v[104:105] op_sel_hi:[1,1,0]
	v_lshlrev_b32_e32 v104, 16, v158
	v_and_b32_e32 v105, 0xffff0000, v158
	v_pk_add_f32 v[170:171], v[114:115], v[114:115] op_sel:[0,1] op_sel_hi:[1,0]
	v_pk_add_f32 v[174:175], v[108:109], v[108:109] op_sel:[0,1] op_sel_hi:[1,0]
	v_pk_mul_f32 v[168:169], v[110:111], v[110:111]
	v_lshlrev_b32_e32 v158, 16, v159
	v_and_b32_e32 v159, 0xffff0000, v159
	v_pk_fma_f32 v[100:101], v[104:105], s[6:7], v[100:101] op_sel_hi:[1,0,1]
	v_pk_fma_f32 v[102:103], v[158:159], s[6:7], v[102:103] op_sel_hi:[1,0,1]
	v_pk_mul_f32 v[158:159], v[100:101], v[100:101]
	v_mov_b32_e32 v171, v168
	v_mov_b32_e32 v175, v169
	v_pk_mul_f32 v[184:185], v[114:115], v[114:115]
	v_lshlrev_b32_e32 v192, 16, v160
	v_and_b32_e32 v193, 0xffff0000, v160
	v_pk_mul_f32 v[166:167], v[102:103], v[102:103]
	v_pk_add_f32 v[168:169], v[170:171], v[174:175]
	v_mov_b32_e32 v170, v100
	v_mov_b32_e32 v171, v158
	v_mov_b32_e32 v158, v101
	v_pk_mul_f32 v[188:189], v[108:109], v[108:109]
	v_lshlrev_b32_e32 v160, 16, v161
	v_and_b32_e32 v161, 0xffff0000, v161
	v_pk_fma_f32 v[104:105], v[192:193], s[6:7], v[96:97] op_sel_hi:[1,0,1]
	v_mov_b32_e32 v192, v110
	v_mov_b32_e32 v193, v184
	v_mov_b32_e32 v184, v111
	v_pk_add_f32 v[158:159], v[170:171], v[158:159]
	v_mov_b32_e32 v170, v102
	v_mov_b32_e32 v171, v166
	v_mov_b32_e32 v166, v103
	v_pk_fma_f32 v[96:97], v[160:161], s[6:7], v[98:99] op_sel_hi:[1,0,1]
	v_pk_mul_f32 v[98:99], v[104:105], v[104:105]
	v_pk_add_f32 v[184:185], v[192:193], v[184:185]
	v_mov_b32_e32 v192, v106
	v_mov_b32_e32 v193, v188
	v_mov_b32_e32 v188, v107
	v_pk_add_f32 v[166:167], v[170:171], v[166:167]
	v_pk_mul_f32 v[160:161], v[96:97], v[96:97]
	v_pk_add_f32 v[188:189], v[192:193], v[188:189]
	v_mov_b32_e32 v190, v141
	v_pk_add_f32 v[158:159], v[158:159], v[166:167]
	v_mov_b32_e32 v166, v104
	v_mov_b32_e32 v167, v98
	v_mov_b32_e32 v98, v105
	v_pk_add_f32 v[184:185], v[184:185], v[188:189]
	v_pk_add_f32 v[168:169], v[168:169], v[190:191]
	v_pk_add_f32 v[98:99], v[166:167], v[98:99]
	v_mov_b32_e32 v166, v96
	v_mov_b32_e32 v167, v160
	v_mov_b32_e32 v160, v97
	v_pk_add_f32 v[168:169], v[184:185], v[168:169]
	v_pk_add_f32 v[160:161], v[166:167], v[160:161]
	v_pk_add_f32 v[158:159], v[168:169], v[158:159]
	v_pk_add_f32 v[98:99], v[98:99], v[160:161]
	ds_bpermute_b32 v164, v180, v162
	v_pk_add_f32 v[98:99], v[158:159], v[98:99]
	ds_bpermute_b32 v165, v180, v163
	ds_bpermute_b32 v158, v181, v98
	ds_bpermute_b32 v159, v181, v99
	v_or_b32_e32 v182, 48, v129
	v_add_u32_e32 v183, 0x3000, v177
	s_waitcnt lgkmcnt(2)
	v_pk_add_f32 v[162:163], v[162:163], v[164:165]
	v_lshl_add_u32 v160, v129, 5, s7
	s_waitcnt lgkmcnt(0)
	v_pk_add_f32 v[164:165], v[98:99], v[158:159]
	v_add_u32_e32 v98, s19, v182
	v_ashrrev_i32_e32 v99, 31, v98
	v_lshlrev_b64 v[98:99], 11, v[98:99]
	v_lshl_add_u64 v[158:159], s[28:29], 0, v[98:99]
	v_lshl_add_u64 v[158:159], v[158:159], 0, s[26:27]
	v_lshl_add_u64 v[158:159], v[158:159], 0, s[24:25]
	v_lshl_add_u64 v[170:171], v[158:159], 0, v[140:141]
	v_cndmask_b32_e32 v200, v183, v160, vcc
	v_mov_b64_e32 v[158:159], v[226:227]
	v_mov_b64_e32 v[160:161], v[228:229]
	s_waitcnt vmcnt(2)
	v_lshlrev_b32_e32 v184, 16, v152
	v_and_b32_e32 v185, 0xffff0000, v152
	v_lshlrev_b32_e32 v152, 16, v153
	v_and_b32_e32 v153, 0xffff0000, v153
	v_lshlrev_b32_e32 v168, 16, v150
	v_and_b32_e32 v169, 0xffff0000, v150
	v_lshlrev_b32_e32 v174, 16, v151
	v_and_b32_e32 v175, 0xffff0000, v151
	v_pk_fma_f32 v[90:91], v[152:153], s[6:7], v[90:91] op_sel_hi:[1,0,1]
	v_pk_fma_f32 v[150:151], v[168:169], s[6:7], v[92:93] op_sel_hi:[1,0,1]
	v_pk_fma_f32 v[92:93], v[174:175], s[6:7], v[94:95] op_sel_hi:[1,0,1]
	v_pk_fma_f32 v[94:95], v[184:185], s[6:7], v[88:89] op_sel_hi:[1,0,1]
	v_mul_f32_e32 v88, v90, v90
	v_pk_fma_f32 v[184:185], v[90:91], v[90:91], v[88:89] op_sel_hi:[1,1,0]
	s_waitcnt vmcnt(1)
; #define PG8_LAS __attribute__((address_space(3)))
;     __device__ __forceinline__ void fused(f32x4 (&acc)[2][2][4][2], const Unit& u, int wr, int wc, int fr, int fq, PG8_LAS unsigned char* lds, int wid, int lane) const {
;     ...
; #pragma unroll
;         for (int ai = 0; ai < 2; ++ai)
; #pragma unroll
;             for (int m = 0; m < 4; ++m) {
;                 const int rl = ai * 128 + wr * 64 + m * 16 + fr;
;                 const size_t roff = (size_t)(u.pm * 256 + rl) * 1024 + u.pn * 256 + wc * 32 + fq * 8;
;                 float s1 = 0.f, s2 = 0.f;
; #pragma unroll
;                 for (int bj = 0; bj < 2; ++bj) {
;                     float x[8];
;                     if (RES_BF16) ld8f((const bfu*)res + roff + bj * 128, x);
;                     else ld8f32((const float*)res + roff + bj * 128, x);
; #pragma unroll
;                     for (int n = 0; n < 2; ++n) {
;                         f32x4 v = acc[ai][bj][m][n];
;                         v[0] += ALPHA * x[4 * n]; v[1] += ALPHA * x[4 * n + 1]; v[2] += ALPHA * x[4 * n + 2]; v[3] += ALPHA * x[4 * n + 3];
;                         acc[ai][bj][m][n] = v;
;                         s1 += (v[0] + v[1]) + (v[2] + v[3]); s2 += (v[0] * v[0] + v[1] * v[1]) + (v[2] * v[2] + v[3] * v[3]);
;                     }
;                 }
;                 s1 += __shfl_xor(s1, 16); s1 += __shfl_xor(s1, 32); s2 += __shfl_xor(s2, 16); s2 += __shfl_xor(s2, 32);
;                 {
;                     PG8_LAS float* pd = (fq == 0) ? P + (rl * 4 + wc) * 2 : (PG8_LAS float*)(lds + 12288) + tid * 2;
;                     pd[0] = s1; pd[1] = s2;
;                 }
;             }
	v_lshlrev_b32_e32 v88, 16, v154
	v_and_b32_e32 v89, 0xffff0000, v154
	v_lshlrev_b32_e32 v192, 16, v155
	v_and_b32_e32 v193, 0xffff0000, v155
	v_lshlrev_b32_e32 v196, 16, v156
	v_and_b32_e32 v197, 0xffff0000, v156
	v_lshlrev_b32_e32 v198, 16, v157
	v_and_b32_e32 v199, 0xffff0000, v157
	v_mov_b64_e32 v[154:155], v[230:231]
	v_mov_b64_e32 v[156:157], v[232:233]
	v_pk_add_f32 v[168:169], v[150:151], v[150:151] op_sel:[0,1] op_sel_hi:[1,0]
	v_pk_add_f32 v[174:175], v[92:93], v[92:93] op_sel:[0,1] op_sel_hi:[1,0]
	v_pk_mul_f32 v[188:189], v[150:151], v[150:151]
	v_pk_mul_f32 v[152:153], v[94:95], v[94:95]
	v_pk_fma_f32 v[84:85], v[88:89], s[6:7], v[84:85] op_sel_hi:[1,0,1]
	v_pk_mul_f32 v[190:191], v[92:93], v[92:93]
	v_pk_fma_f32 v[86:87], v[192:193], s[6:7], v[86:87] op_sel_hi:[1,0,1]
	v_pk_mul_f32 v[170:171], v[84:85], v[84:85]
	v_pk_fma_f32 v[88:89], v[196:197], s[6:7], v[80:81] op_sel_hi:[1,0,1]
	v_pk_fma_f32 v[80:81], v[198:199], s[6:7], v[82:83] op_sel_hi:[1,0,1]
	v_mov_b32_e32 v198, v94
	v_mov_b32_e32 v199, v188
	v_mov_b32_e32 v188, v95
	v_mov_b32_e32 v169, v152
	v_mov_b32_e32 v175, v153
	v_pk_mul_f32 v[192:193], v[86:87], v[86:87]
	v_pk_add_f32 v[188:189], v[198:199], v[188:189]
	v_mov_b32_e32 v198, v90
	v_mov_b32_e32 v199, v190
	v_mov_b32_e32 v190, v91
	v_pk_add_f32 v[152:153], v[168:169], v[174:175]
	v_mov_b32_e32 v168, v84
	v_mov_b32_e32 v169, v170
	v_mov_b32_e32 v170, v85
	v_pk_add_f32 v[190:191], v[198:199], v[190:191]
	v_mov_b32_e32 v184, v141
	v_pk_add_f32 v[168:169], v[168:169], v[170:171]
	v_mov_b32_e32 v170, v86
	v_mov_b32_e32 v171, v192
	v_mov_b32_e32 v192, v87
	v_pk_add_f32 v[188:189], v[188:189], v[190:191]
	v_pk_add_f32 v[152:153], v[152:153], v[184:185]
	v_pk_add_f32 v[170:171], v[170:171], v[192:193]
	v_pk_mul_f32 v[82:83], v[88:89], v[88:89]
	v_pk_add_f32 v[152:153], v[188:189], v[152:153]
	v_pk_add_f32 v[168:169], v[168:169], v[170:171]
	v_pk_mul_f32 v[196:197], v[80:81], v[80:81]
	v_pk_add_f32 v[152:153], v[152:153], v[168:169]
	v_mov_b32_e32 v168, v88
	v_mov_b32_e32 v169, v82
	v_mov_b32_e32 v82, v89
	v_pk_add_f32 v[82:83], v[168:169], v[82:83]
	v_mov_b32_e32 v168, v80
	v_mov_b32_e32 v169, v196
	v_mov_b32_e32 v196, v81
	v_pk_add_f32 v[168:169], v[168:169], v[196:197]
	v_add_u32_e32 v188, 0x80, v129
	v_pk_add_f32 v[82:83], v[82:83], v[168:169]
	ds_bpermute_b32 v166, v180, v164
	v_pk_add_f32 v[82:83], v[152:153], v[82:83]
	ds_bpermute_b32 v152, v181, v82
	ds_bpermute_b32 v153, v181, v83
	ds_bpermute_b32 v167, v180, v165
	ds_write_b64 v200, v[162:163]
	v_lshl_add_u32 v162, v178, 5, s7
	v_cndmask_b32_e32 v189, v183, v162, vcc
	s_waitcnt lgkmcnt(2)
	v_pk_add_f32 v[168:169], v[82:83], v[152:153]
	v_add_u32_e32 v82, s19, v188
	v_ashrrev_i32_e32 v83, 31, v82
	s_waitcnt vmcnt(1)
	v_lshlrev_b32_e32 v184, 16, v160
	v_and_b32_e32 v185, 0xffff0000, v160
	v_lshlrev_b32_e32 v160, 16, v161
	v_and_b32_e32 v161, 0xffff0000, v161
	v_lshlrev_b32_e32 v152, 16, v158
	v_lshlrev_b64 v[82:83], 11, v[82:83]
	v_and_b32_e32 v153, 0xffff0000, v158
	v_lshlrev_b32_e32 v158, 16, v159
	v_and_b32_e32 v159, 0xffff0000, v159
	v_pk_fma_f32 v[74:75], v[160:161], s[6:7], v[74:75] op_sel_hi:[1,0,1]
	v_lshl_add_u64 v[162:163], s[28:29], 0, v[82:83]
	v_pk_fma_f32 v[152:153], v[152:153], s[6:7], v[76:77] op_sel_hi:[1,0,1]
	v_pk_fma_f32 v[76:77], v[158:159], s[6:7], v[78:79] op_sel_hi:[1,0,1]
	v_pk_fma_f32 v[78:79], v[184:185], s[6:7], v[72:73] op_sel_hi:[1,0,1]
	v_mul_f32_e32 v72, v74, v74
	v_lshl_add_u64 v[162:163], v[162:163], 0, s[26:27]
	v_pk_add_f32 v[190:191], v[152:153], v[152:153] op_sel:[0,1] op_sel_hi:[1,0]
	v_pk_add_f32 v[192:193], v[76:77], v[76:77] op_sel:[0,1] op_sel_hi:[1,0]
	v_pk_mul_f32 v[160:161], v[78:79], v[78:79]
	v_pk_fma_f32 v[184:185], v[74:75], v[74:75], v[72:73] op_sel_hi:[1,1,0]
	s_waitcnt vmcnt(0)
	v_lshlrev_b32_e32 v72, 16, v154
	v_and_b32_e32 v73, 0xffff0000, v154
	v_lshl_add_u64 v[162:163], v[162:163], 0, s[24:25]
	v_pk_mul_f32 v[196:197], v[152:153], v[152:153]
	v_lshlrev_b32_e32 v154, 16, v155
	v_and_b32_e32 v155, 0xffff0000, v155
	v_lshlrev_b32_e32 v200, 16, v156
	v_and_b32_e32 v201, 0xffff0000, v156
	v_lshlrev_b32_e32 v202, 16, v157
	v_and_b32_e32 v203, 0xffff0000, v157
	v_pk_fma_f32 v[68:69], v[72:73], s[6:7], v[68:69] op_sel_hi:[1,0,1]
	v_mov_b32_e32 v191, v160
	v_mov_b32_e32 v193, v161
	v_lshl_add_u64 v[174:175], v[162:163], 0, v[140:141]
	v_pk_mul_f32 v[198:199], v[76:77], v[76:77]
	v_pk_fma_f32 v[70:71], v[154:155], s[6:7], v[70:71] op_sel_hi:[1,0,1]
	v_pk_mul_f32 v[154:155], v[68:69], v[68:69]
	v_pk_fma_f32 v[72:73], v[200:201], s[6:7], v[64:65] op_sel_hi:[1,0,1]
	v_pk_fma_f32 v[64:65], v[202:203], s[6:7], v[66:67] op_sel_hi:[1,0,1]
	v_mov_b32_e32 v202, v78
	v_mov_b32_e32 v203, v196
	v_mov_b32_e32 v196, v79
	v_pk_add_f32 v[160:161], v[190:191], v[192:193]
	v_mov_b32_e32 v184, v141
	s_waitcnt lgkmcnt(1)
	v_pk_add_f32 v[166:167], v[164:165], v[166:167]
	v_mov_b64_e32 v[162:163], v[234:235]
	v_mov_b64_e32 v[164:165], v[236:237]
	v_mov_b64_e32 v[156:157], v[238:239]
	v_mov_b64_e32 v[158:159], v[240:241]
	v_pk_mul_f32 v[174:175], v[70:71], v[70:71]
	v_pk_add_f32 v[196:197], v[202:203], v[196:197]
	v_mov_b32_e32 v202, v74
	v_mov_b32_e32 v203, v198
	v_mov_b32_e32 v198, v75
	v_pk_add_f32 v[160:161], v[160:161], v[184:185]
	v_mov_b32_e32 v184, v68
	v_mov_b32_e32 v185, v154
	v_mov_b32_e32 v154, v69
	v_pk_add_f32 v[198:199], v[202:203], v[198:199]
	v_pk_add_f32 v[154:155], v[184:185], v[154:155]
	v_mov_b32_e32 v184, v70
	v_mov_b32_e32 v185, v174
	v_mov_b32_e32 v174, v71
	v_pk_add_f32 v[196:197], v[196:197], v[198:199]
	v_pk_add_f32 v[174:175], v[184:185], v[174:175]
	v_pk_mul_f32 v[66:67], v[72:73], v[72:73]
	v_pk_add_f32 v[160:161], v[196:197], v[160:161]
	v_pk_add_f32 v[154:155], v[154:155], v[174:175]
	v_pk_mul_f32 v[200:201], v[64:65], v[64:65]
	v_pk_add_f32 v[154:155], v[160:161], v[154:155]
	v_mov_b32_e32 v160, v72
	v_mov_b32_e32 v161, v66
	v_mov_b32_e32 v66, v73
	v_pk_add_f32 v[66:67], v[160:161], v[66:67]
	v_mov_b32_e32 v160, v64
	v_mov_b32_e32 v161, v200
	v_mov_b32_e32 v200, v65
	v_pk_add_f32 v[160:161], v[160:161], v[200:201]
	ds_write_b64 v189, v[166:167]
	v_pk_add_f32 v[66:67], v[66:67], v[160:161]
	v_add_u32_e32 v189, 0x90, v129
	v_pk_add_f32 v[66:67], v[154:155], v[66:67]
	ds_bpermute_b32 v154, v181, v66
	ds_bpermute_b32 v155, v181, v67
	ds_bpermute_b32 v170, v180, v168
	ds_bpermute_b32 v171, v180, v169
	v_lshl_add_u32 v160, v179, 5, s7
	v_cndmask_b32_e32 v206, v183, v160, vcc
	s_waitcnt lgkmcnt(2)
; #define PG8_LAS __attribute__((address_space(3)))
;     __device__ __forceinline__ void fused(f32x4 (&acc)[2][2][4][2], const Unit& u, int wr, int wc, int fr, int fq, PG8_LAS unsigned char* lds, int wid, int lane) const {
;     ...
; #pragma unroll
;         for (int ai = 0; ai < 2; ++ai)
; #pragma unroll
;             for (int m = 0; m < 4; ++m) {
;                 const int rl = ai * 128 + wr * 64 + m * 16 + fr;
;                 const size_t roff = (size_t)(u.pm * 256 + rl) * 1024 + u.pn * 256 + wc * 32 + fq * 8;
;                 float s1 = 0.f, s2 = 0.f;
; #pragma unroll
;                 for (int bj = 0; bj < 2; ++bj) {
;                     float x[8];
;                     if (RES_BF16) ld8f((const bfu*)res + roff + bj * 128, x);
;                     else ld8f32((const float*)res + roff + bj * 128, x);
; #pragma unroll
;                     for (int n = 0; n < 2; ++n) {
;                         f32x4 v = acc[ai][bj][m][n];
;                         v[0] += ALPHA * x[4 * n]; v[1] += ALPHA * x[4 * n + 1]; v[2] += ALPHA * x[4 * n + 2]; v[3] += ALPHA * x[4 * n + 3];
;                         acc[ai][bj][m][n] = v;
;                         s1 += (v[0] + v[1]) + (v[2] + v[3]); s2 += (v[0] * v[0] + v[1] * v[1]) + (v[2] * v[2] + v[3] * v[3]);
;                     }
;                 }
;                 s1 += __shfl_xor(s1, 16); s1 += __shfl_xor(s1, 32); s2 += __shfl_xor(s2, 16); s2 += __shfl_xor(s2, 32);
;                 {
;                     PG8_LAS float* pd = (fq == 0) ? P + (rl * 4 + wc) * 2 : (PG8_LAS float*)(lds + 12288) + tid * 2;
;                     pd[0] = s1; pd[1] = s2;
;                 }
;             }
	v_pk_add_f32 v[174:175], v[66:67], v[154:155]
	v_add_u32_e32 v66, s19, v189
	v_ashrrev_i32_e32 v67, 31, v66
	v_lshlrev_b64 v[66:67], 11, v[66:67]
	v_lshl_add_u64 v[160:161], s[28:29], 0, v[66:67]
	v_lshl_add_u64 v[160:161], v[160:161], 0, s[26:27]
	v_lshl_add_u64 v[160:161], v[160:161], 0, s[24:25]
	v_lshl_add_u64 v[160:161], v[160:161], 0, v[140:141]
	s_waitcnt lgkmcnt(0)
	v_pk_add_f32 v[170:171], v[168:169], v[170:171]
	v_mov_b64_e32 v[166:167], v[242:243]
	v_mov_b64_e32 v[168:169], v[244:245]
	ds_bpermute_b32 v184, v180, v174
	ds_bpermute_b32 v185, v180, v175
	ds_write_b64 v206, v[170:171]
	s_waitcnt lgkmcnt(1)
	v_pk_add_f32 v[170:171], v[174:175], v[184:185]
	s_waitcnt vmcnt(2)
	v_lshlrev_b32_e32 v190, 16, v164
	v_and_b32_e32 v191, 0xffff0000, v164
	v_lshlrev_b32_e32 v164, 16, v165
	v_and_b32_e32 v165, 0xffff0000, v165
	v_lshlrev_b32_e32 v154, 16, v162
	v_and_b32_e32 v155, 0xffff0000, v162
	v_lshlrev_b32_e32 v162, 16, v163
	v_and_b32_e32 v163, 0xffff0000, v163
	v_pk_fma_f32 v[58:59], v[164:165], s[6:7], v[58:59] op_sel_hi:[1,0,1]
	v_pk_fma_f32 v[154:155], v[154:155], s[6:7], v[60:61] op_sel_hi:[1,0,1]
	v_pk_fma_f32 v[60:61], v[162:163], s[6:7], v[62:63] op_sel_hi:[1,0,1]
	v_pk_fma_f32 v[62:63], v[190:191], s[6:7], v[56:57] op_sel_hi:[1,0,1]
	v_mul_f32_e32 v56, v58, v58
	v_pk_fma_f32 v[190:191], v[58:59], v[58:59], v[56:57] op_sel_hi:[1,1,0]
	s_waitcnt vmcnt(1)
	v_lshlrev_b32_e32 v56, 16, v156
	v_and_b32_e32 v57, 0xffff0000, v156
	v_lshlrev_b32_e32 v200, 16, v158
	v_and_b32_e32 v201, 0xffff0000, v158
	v_lshlrev_b32_e32 v202, 16, v159
	v_and_b32_e32 v203, 0xffff0000, v159
	v_mov_b64_e32 v[158:159], v[246:247]
	v_mov_b64_e32 v[160:161], v[248:249]
	v_pk_mul_f32 v[196:197], v[154:155], v[154:155]
	v_lshlrev_b32_e32 v156, 16, v157
	v_and_b32_e32 v157, 0xffff0000, v157
	v_pk_fma_f32 v[52:53], v[56:57], s[6:7], v[52:53] op_sel_hi:[1,0,1]
	v_pk_add_f32 v[162:163], v[154:155], v[154:155] op_sel:[0,1] op_sel_hi:[1,0]
	v_pk_add_f32 v[192:193], v[60:61], v[60:61] op_sel:[0,1] op_sel_hi:[1,0]
	v_pk_mul_f32 v[198:199], v[60:61], v[60:61]
	v_pk_mul_f32 v[164:165], v[62:63], v[62:63]
	v_pk_fma_f32 v[54:55], v[156:157], s[6:7], v[54:55] op_sel_hi:[1,0,1]
	v_pk_mul_f32 v[156:157], v[52:53], v[52:53]
	v_pk_fma_f32 v[56:57], v[200:201], s[6:7], v[48:49] op_sel_hi:[1,0,1]
	v_pk_fma_f32 v[48:49], v[202:203], s[6:7], v[50:51] op_sel_hi:[1,0,1]
	v_mov_b32_e32 v202, v62
	v_mov_b32_e32 v203, v196
	v_mov_b32_e32 v196, v63
	v_pk_mul_f32 v[204:205], v[54:55], v[54:55]
	v_pk_add_f32 v[196:197], v[202:203], v[196:197]
	v_mov_b32_e32 v202, v58
	v_mov_b32_e32 v203, v198
	v_mov_b32_e32 v198, v59
	v_mov_b32_e32 v163, v164
	v_mov_b32_e32 v193, v165
	v_mov_b32_e32 v164, v52
	v_mov_b32_e32 v165, v156
	v_mov_b32_e32 v156, v53
	v_pk_add_f32 v[198:199], v[202:203], v[198:199]
	v_pk_add_f32 v[162:163], v[162:163], v[192:193]
	v_mov_b32_e32 v190, v141
	v_pk_add_f32 v[156:157], v[164:165], v[156:157]
	v_mov_b32_e32 v164, v54
	v_mov_b32_e32 v165, v204
	v_mov_b32_e32 v204, v55
	v_pk_add_f32 v[196:197], v[196:197], v[198:199]
	v_pk_add_f32 v[162:163], v[162:163], v[190:191]
	v_pk_add_f32 v[164:165], v[164:165], v[204:205]
	v_pk_mul_f32 v[50:51], v[56:57], v[56:57]
	v_pk_add_f32 v[162:163], v[196:197], v[162:163]
	v_pk_add_f32 v[156:157], v[156:157], v[164:165]
	v_pk_mul_f32 v[200:201], v[48:49], v[48:49]
	v_pk_add_f32 v[156:157], v[162:163], v[156:157]
	v_mov_b32_e32 v162, v56
	v_mov_b32_e32 v163, v50
	v_mov_b32_e32 v50, v57
	v_pk_add_f32 v[50:51], v[162:163], v[50:51]
	v_mov_b32_e32 v162, v48
	v_mov_b32_e32 v163, v200
	v_mov_b32_e32 v200, v49
	v_pk_add_f32 v[162:163], v[162:163], v[200:201]
	v_add_u32_e32 v190, 0xa0, v129
	v_pk_add_f32 v[50:51], v[50:51], v[162:163]
	v_lshl_add_u32 v162, v182, 5, s7
	v_pk_add_f32 v[50:51], v[156:157], v[50:51]
	ds_bpermute_b32 v156, v181, v50
	ds_bpermute_b32 v157, v181, v51
	v_cndmask_b32_e32 v191, v183, v162, vcc
	s_waitcnt vmcnt(1)
	v_lshlrev_b32_e32 v162, 16, v168
	v_and_b32_e32 v163, 0xffff0000, v168
	ds_write_b64 v191, v[170:171]
	s_waitcnt lgkmcnt(1)
	v_pk_add_f32 v[174:175], v[50:51], v[156:157]
	v_lshlrev_b32_e32 v50, 16, v166
	v_and_b32_e32 v51, 0xffff0000, v166
	v_lshlrev_b32_e32 v156, 16, v167
	v_and_b32_e32 v157, 0xffff0000, v167
	v_pk_fma_f32 v[50:51], v[50:51], s[6:7], v[44:45] op_sel_hi:[1,0,1]
	v_pk_fma_f32 v[44:45], v[156:157], s[6:7], v[46:47] op_sel_hi:[1,0,1]
	v_pk_fma_f32 v[46:47], v[162:163], s[6:7], v[40:41] op_sel_hi:[1,0,1]
	v_add_u32_e32 v40, s19, v190
	v_ashrrev_i32_e32 v41, 31, v40
	v_lshlrev_b64 v[156:157], 11, v[40:41]
	v_lshl_add_u64 v[40:41], s[28:29], 0, v[156:157]
	v_lshl_add_u64 v[40:41], v[40:41], 0, s[26:27]
	v_lshl_add_u64 v[40:41], v[40:41], 0, s[24:25]
	v_lshlrev_b32_e32 v166, 16, v169
	v_and_b32_e32 v167, 0xffff0000, v169
	v_lshl_add_u64 v[168:169], v[40:41], 0, v[140:141]
	global_load_dwordx4 v[162:165], v[168:169], off
	v_pk_fma_f32 v[42:43], v[166:167], s[6:7], v[42:43] op_sel_hi:[1,0,1]
	v_pk_add_f32 v[192:193], v[50:51], v[50:51] op_sel:[0,1] op_sel_hi:[1,0]
	v_mul_f32_e32 v40, v42, v42
	v_pk_fma_f32 v[204:205], v[42:43], v[42:43], v[40:41] op_sel_hi:[1,1,0]
	s_waitcnt vmcnt(1)
; #define PG8_LAS __attribute__((address_space(3)))
;     __device__ __forceinline__ void fused(f32x4 (&acc)[2][2][4][2], const Unit& u, int wr, int wc, int fr, int fq, PG8_LAS unsigned char* lds, int wid, int lane) const {
;     ...
; #pragma unroll
;         for (int ai = 0; ai < 2; ++ai)
; #pragma unroll
;             for (int m = 0; m < 4; ++m) {
;                 const int rl = ai * 128 + wr * 64 + m * 16 + fr;
;                 const size_t roff = (size_t)(u.pm * 256 + rl) * 1024 + u.pn * 256 + wc * 32 + fq * 8;
;                 float s1 = 0.f, s2 = 0.f;
; #pragma unroll
;                 for (int bj = 0; bj < 2; ++bj) {
;                     float x[8];
;                     if (RES_BF16) ld8f((const bfu*)res + roff + bj * 128, x);
;                     else ld8f32((const float*)res + roff + bj * 128, x);
; #pragma unroll
;                     for (int n = 0; n < 2; ++n) {
;                         f32x4 v = acc[ai][bj][m][n];
;                         v[0] += ALPHA * x[4 * n]; v[1] += ALPHA * x[4 * n + 1]; v[2] += ALPHA * x[4 * n + 2]; v[3] += ALPHA * x[4 * n + 3];
;                         acc[ai][bj][m][n] = v;
;                         s1 += (v[0] + v[1]) + (v[2] + v[3]); s2 += (v[0] * v[0] + v[1] * v[1]) + (v[2] * v[2] + v[3] * v[3]);
;                     }
;                 }
;                 s1 += __shfl_xor(s1, 16); s1 += __shfl_xor(s1, 32); s2 += __shfl_xor(s2, 16); s2 += __shfl_xor(s2, 32);
;                 {
;                     PG8_LAS float* pd = (fq == 0) ? P + (rl * 4 + wc) * 2 : (PG8_LAS float*)(lds + 12288) + tid * 2;
;                     pd[0] = s1; pd[1] = s2;
;                 }
;             }
	v_lshlrev_b32_e32 v40, 16, v158
	v_and_b32_e32 v41, 0xffff0000, v158
	v_pk_add_f32 v[196:197], v[44:45], v[44:45] op_sel:[0,1] op_sel_hi:[1,0]
	v_pk_mul_f32 v[198:199], v[50:51], v[50:51]
	v_pk_mul_f32 v[202:203], v[46:47], v[46:47]
	v_lshlrev_b32_e32 v158, 16, v159
	v_and_b32_e32 v159, 0xffff0000, v159
	v_pk_fma_f32 v[40:41], v[40:41], s[6:7], v[36:37] op_sel_hi:[1,0,1]
	v_pk_mul_f32 v[200:201], v[44:45], v[44:45]
	v_pk_fma_f32 v[36:37], v[158:159], s[6:7], v[38:39] op_sel_hi:[1,0,1]
	v_pk_mul_f32 v[158:159], v[40:41], v[40:41]
	v_mov_b32_e32 v208, v46
	v_mov_b32_e32 v209, v198
	v_mov_b32_e32 v198, v47
	v_mov_b32_e32 v193, v202
	v_mov_b32_e32 v197, v203
	v_pk_mul_f32 v[206:207], v[36:37], v[36:37]
	v_pk_add_f32 v[198:199], v[208:209], v[198:199]
	v_mov_b32_e32 v208, v42
	v_mov_b32_e32 v209, v200
	v_mov_b32_e32 v200, v43
	v_pk_add_f32 v[192:193], v[192:193], v[196:197]
	v_mov_b32_e32 v196, v40
	v_mov_b32_e32 v197, v158
	v_mov_b32_e32 v158, v41
	v_lshlrev_b32_e32 v166, 16, v160
	v_and_b32_e32 v167, 0xffff0000, v160
	v_pk_add_f32 v[200:201], v[208:209], v[200:201]
	v_mov_b32_e32 v204, v141
	v_pk_add_f32 v[158:159], v[196:197], v[158:159]
	v_mov_b32_e32 v196, v36
	v_mov_b32_e32 v197, v206
	v_mov_b32_e32 v206, v37
	v_lshlrev_b32_e32 v160, 16, v161
	v_and_b32_e32 v161, 0xffff0000, v161
	v_pk_fma_f32 v[38:39], v[166:167], s[6:7], v[32:33] op_sel_hi:[1,0,1]
	v_pk_add_f32 v[198:199], v[198:199], v[200:201]
	v_pk_add_f32 v[192:193], v[192:193], v[204:205]
	v_pk_add_f32 v[196:197], v[196:197], v[206:207]
	v_pk_fma_f32 v[32:33], v[160:161], s[6:7], v[34:35] op_sel_hi:[1,0,1]
	v_pk_mul_f32 v[34:35], v[38:39], v[38:39]
	v_pk_add_f32 v[192:193], v[198:199], v[192:193]
	v_pk_add_f32 v[158:159], v[158:159], v[196:197]
	v_pk_mul_f32 v[160:161], v[32:33], v[32:33]
	v_pk_add_f32 v[158:159], v[192:193], v[158:159]
	v_mov_b32_e32 v192, v38
	v_mov_b32_e32 v193, v34
	v_mov_b32_e32 v34, v39
	v_pk_add_f32 v[34:35], v[192:193], v[34:35]
	v_mov_b32_e32 v192, v32
	v_mov_b32_e32 v193, v160
	v_mov_b32_e32 v160, v33
	v_pk_add_f32 v[160:161], v[192:193], v[160:161]
	global_load_dwordx4 v[166:169], v[168:169], off offset:256
	v_pk_add_f32 v[34:35], v[34:35], v[160:161]
	ds_bpermute_b32 v184, v180, v174
	v_pk_add_f32 v[34:35], v[158:159], v[34:35]
	ds_bpermute_b32 v158, v181, v34
	ds_bpermute_b32 v159, v181, v35
	ds_bpermute_b32 v185, v180, v175
	v_add_u32_e32 v191, 0xb0, v129
	v_lshl_add_u32 v160, v188, 5, s7
	v_cndmask_b32_e32 v192, v183, v160, vcc
	s_waitcnt lgkmcnt(1)
	v_pk_add_f32 v[158:159], v[34:35], v[158:159]
	v_add_u32_e32 v34, s19, v191
	v_ashrrev_i32_e32 v35, 31, v34
	ds_bpermute_b32 v170, v180, v158
	ds_bpermute_b32 v171, v180, v159
	v_lshlrev_b64 v[34:35], 11, v[34:35]
	s_waitcnt lgkmcnt(2)
	v_pk_add_f32 v[160:161], v[174:175], v[184:185]
	v_lshl_add_u64 v[174:175], s[28:29], 0, v[34:35]
	v_lshl_add_u64 v[174:175], v[174:175], 0, s[26:27]
	v_lshl_add_u64 v[174:175], v[174:175], 0, s[24:25]
	v_lshl_add_u64 v[174:175], v[174:175], 0, v[140:141]
	v_lshl_add_u32 v140, v189, 5, s7
	global_load_dwordx4 v[196:199], v[174:175], off
	v_cndmask_b32_e32 v140, v183, v140, vcc
	s_waitcnt lgkmcnt(0)
	v_pk_add_f32 v[158:159], v[158:159], v[170:171]
	ds_write_b64 v192, v[160:161]
	ds_write_b64 v140, v[158:159]
	s_waitcnt vmcnt(2)
	v_lshlrev_b32_e32 v158, 16, v162
	v_and_b32_e32 v159, 0xffff0000, v162
	v_lshlrev_b32_e32 v162, 16, v163
	v_and_b32_e32 v163, 0xffff0000, v163
	v_pk_fma_f32 v[160:161], v[158:159], s[6:7], v[28:29] op_sel_hi:[1,0,1]
	v_pk_fma_f32 v[158:159], v[162:163], s[6:7], v[30:31] op_sel_hi:[1,0,1]
	global_load_dwordx4 v[28:31], v[174:175], off offset:256
	v_lshlrev_b32_e32 v184, 16, v165
	v_and_b32_e32 v185, 0xffff0000, v165
	v_lshlrev_b32_e32 v170, 16, v164
	v_and_b32_e32 v171, 0xffff0000, v164
	v_pk_fma_f32 v[162:163], v[184:185], s[6:7], v[26:27] op_sel_hi:[1,0,1]
	v_pk_fma_f32 v[164:165], v[170:171], s[6:7], v[24:25] op_sel_hi:[1,0,1]
	v_mul_f32_e32 v24, v162, v162
	v_pk_add_f32 v[192:193], v[160:161], v[160:161] op_sel:[0,1] op_sel_hi:[1,0]
	v_pk_add_f32 v[200:201], v[158:159], v[158:159] op_sel:[0,1] op_sel_hi:[1,0]
	v_pk_mul_f32 v[26:27], v[164:165], v[164:165]
	v_pk_fma_f32 v[170:171], v[162:163], v[162:163], v[24:25] op_sel_hi:[1,1,0]
	v_pk_mul_f32 v[202:203], v[160:161], v[160:161]
	v_mov_b32_e32 v193, v26
	v_mov_b32_e32 v201, v27
	v_pk_mul_f32 v[174:175], v[158:159], v[158:159]
	v_pk_add_f32 v[26:27], v[192:193], v[200:201]
	v_mov_b32_e32 v170, v141
	v_pk_add_f32 v[26:27], v[26:27], v[170:171]
	v_lshl_add_u32 v140, v190, 5, s7
	s_waitcnt vmcnt(2)
	v_lshlrev_b32_e32 v24, 16, v166
	v_and_b32_e32 v25, 0xffff0000, v166
	v_lshlrev_b32_e32 v166, 16, v167
	v_and_b32_e32 v167, 0xffff0000, v167
	v_lshlrev_b32_e32 v184, 16, v168
	v_and_b32_e32 v185, 0xffff0000, v168
	v_pk_fma_f32 v[24:25], v[24:25], s[6:7], v[20:21] op_sel_hi:[1,0,1]
	v_pk_fma_f32 v[20:21], v[166:167], s[6:7], v[22:23] op_sel_hi:[1,0,1]
	v_pk_mul_f32 v[166:167], v[24:25], v[24:25]
	v_pk_fma_f32 v[22:23], v[184:185], s[6:7], v[16:17] op_sel_hi:[1,0,1]
	v_mov_b32_e32 v184, v164
	v_mov_b32_e32 v185, v202
	v_mov_b32_e32 v202, v165
	v_pk_mul_f32 v[204:205], v[20:21], v[20:21]
	v_pk_add_f32 v[184:185], v[184:185], v[202:203]
	v_mov_b32_e32 v202, v162
	v_mov_b32_e32 v203, v174
	v_mov_b32_e32 v174, v163
	v_mov_b32_e32 v170, v24
	v_mov_b32_e32 v171, v166
	v_mov_b32_e32 v166, v25
	v_pk_add_f32 v[174:175], v[202:203], v[174:175]
	v_pk_add_f32 v[166:167], v[170:171], v[166:167]
	v_mov_b32_e32 v170, v20
	v_mov_b32_e32 v171, v204
	v_mov_b32_e32 v204, v21
	v_lshlrev_b32_e32 v168, 16, v169
	v_and_b32_e32 v169, 0xffff0000, v169
	v_pk_add_f32 v[174:175], v[184:185], v[174:175]
	v_pk_add_f32 v[170:171], v[170:171], v[204:205]
	v_pk_fma_f32 v[16:17], v[168:169], s[6:7], v[18:19] op_sel_hi:[1,0,1]
	v_pk_mul_f32 v[18:19], v[22:23], v[22:23]
	v_pk_add_f32 v[26:27], v[174:175], v[26:27]
	v_pk_add_f32 v[166:167], v[166:167], v[170:171]
	v_pk_mul_f32 v[168:169], v[16:17], v[16:17]
	v_pk_add_f32 v[26:27], v[26:27], v[166:167]
	v_mov_b32_e32 v166, v22
	v_mov_b32_e32 v167, v18
	v_mov_b32_e32 v18, v23
	v_pk_add_f32 v[18:19], v[166:167], v[18:19]
	v_mov_b32_e32 v166, v16
	v_mov_b32_e32 v167, v168
	v_mov_b32_e32 v168, v17
	v_pk_add_f32 v[166:167], v[166:167], v[168:169]
	s_waitcnt vmcnt(1)
; #define PG8_LAS __attribute__((address_space(3)))
; __device__ __forceinline__ unsigned xb_ld(unsigned* p)              { return __hip_atomic_load(p, __ATOMIC_RELAXED, __HIP_MEMORY_SCOPE_AGENT); }
; __device__ __forceinline__ unsigned xb_add(unsigned* p, unsigned v) { return __hip_atomic_fetch_add(p, v, __ATOMIC_RELAXED, __HIP_MEMORY_SCOPE_AGENT); }
; #define XB_SPIN(cond, bar) do { unsigned _sp = 0; while (cond) { __builtin_amdgcn_s_sleep(1); \
;     if ((++_sp & 255u) == 0u) { if (xb_ld(&(bar)[XB_TMO])) break; if (_sp > XB_SPIN_CAP) { atomicAdd(&(bar)[XB_TMO], 1u); break; } } } } while (0)
;     __device__ __forceinline__ void fused(f32x4 (&acc)[2][2][4][2], const Unit& u, int wr, int wc, int fr, int fq, PG8_LAS unsigned char* lds, int wid, int lane) const {
;     ...
;                 s1 += __shfl_xor(s1, 16); s1 += __shfl_xor(s1, 32); s2 += __shfl_xor(s2, 16); s2 += __shfl_xor(s2, 32);
;                 {
;                     PG8_LAS float* pd = (fq == 0) ? P + (rl * 4 + wc) * 2 : (PG8_LAS float*)(lds + 12288) + tid * 2;
;                     pd[0] = s1; pd[1] = s2;
;                 }
;             }
;         __syncthreads();
;         if (tid < 256) {
;             const float a = P[tid * 8] + P[tid * 8 + 2] + P[tid * 8 + 4] + P[tid * 8 + 6], b = P[tid * 8 + 1] + P[tid * 8 + 3] + P[tid * 8 + 5] + P[tid * 8 + 7];
;             const unsigned long long pk = (unsigned long long)__float_as_uint(a) | ((unsigned long long)__float_as_uint(b) << 32);
;             __hip_atomic_store(xch + ((size_t)(u.pm * 256 + tid) * 4 + u.pn), pk, __ATOMIC_RELAXED, __HIP_MEMORY_SCOPE_AGENT);
;         }
;         asm volatile("s_waitcnt vmcnt(0)" ::: "memory");
;         __syncthreads();
;         if (tid == 0) {
;             __builtin_amdgcn_fence(__ATOMIC_RELEASE, "agent");
;             asm volatile("s_waitcnt vmcnt(0)" ::: "memory");
;             unsigned* c = cnt + u.pm * 64;
;             xb_add(c, 1u);
;             XB_SPIN(xb_ld(c) < 4u, bar);
;             __builtin_amdgcn_fence(__ATOMIC_ACQUIRE, "agent");
;             asm volatile("s_waitcnt vmcnt(0)" ::: "memory");
;         }
	v_lshlrev_b32_e32 v168, 16, v198
	v_pk_add_f32 v[18:19], v[18:19], v[166:167]
	v_and_b32_e32 v169, 0xffff0000, v198
	v_pk_add_f32 v[184:185], v[26:27], v[18:19]
	v_lshlrev_b32_e32 v18, 16, v196
	v_and_b32_e32 v19, 0xffff0000, v196
	v_lshlrev_b32_e32 v26, 16, v197
	v_and_b32_e32 v27, 0xffff0000, v197
	v_lshlrev_b32_e32 v196, 16, v199
	v_and_b32_e32 v197, 0xffff0000, v199
	v_pk_fma_f32 v[170:171], v[18:19], s[6:7], v[12:13] op_sel_hi:[1,0,1]
	v_pk_fma_f32 v[166:167], v[26:27], s[6:7], v[14:15] op_sel_hi:[1,0,1]
	v_pk_fma_f32 v[174:175], v[168:169], s[6:7], v[8:9] op_sel_hi:[1,0,1]
	v_pk_fma_f32 v[168:169], v[196:197], s[6:7], v[10:11] op_sel_hi:[1,0,1]
	v_pk_add_f32 v[12:13], v[170:171], v[170:171] op_sel:[0,1] op_sel_hi:[1,0]
	v_pk_add_f32 v[14:15], v[166:167], v[166:167] op_sel:[0,1] op_sel_hi:[1,0]
	v_pk_mul_f32 v[8:9], v[174:175], v[174:175]
	v_mul_f32_e32 v10, v168, v168
	s_waitcnt vmcnt(0)
	v_lshlrev_b32_e32 v18, 16, v28
	v_and_b32_e32 v19, 0xffff0000, v28
	v_pk_fma_f32 v[10:11], v[168:169], v[168:169], v[10:11] op_sel_hi:[1,1,0]
	v_lshlrev_b32_e32 v28, 16, v29
	v_and_b32_e32 v29, 0xffff0000, v29
	v_pk_fma_f32 v[26:27], v[18:19], s[6:7], v[4:5] op_sel_hi:[1,0,1]
	v_mov_b32_e32 v13, v8
	v_mov_b32_e32 v15, v9
	v_pk_fma_f32 v[18:19], v[28:29], s[6:7], v[6:7] op_sel_hi:[1,0,1]
	v_pk_mul_f32 v[4:5], v[26:27], v[26:27]
	v_pk_add_f32 v[8:9], v[12:13], v[14:15]
	v_mov_b32_e32 v10, v141
	v_pk_mul_f32 v[198:199], v[170:171], v[170:171]
	v_lshlrev_b32_e32 v196, 16, v30
	v_and_b32_e32 v197, 0xffff0000, v30
	v_pk_mul_f32 v[6:7], v[18:19], v[18:19]
	v_pk_add_f32 v[8:9], v[8:9], v[10:11]
	v_mov_b32_e32 v10, v26
	v_mov_b32_e32 v11, v4
	v_mov_b32_e32 v4, v27
	v_pk_mul_f32 v[200:201], v[166:167], v[166:167]
	v_lshlrev_b32_e32 v202, 16, v31
	v_and_b32_e32 v203, 0xffff0000, v31
	v_pk_fma_f32 v[30:31], v[196:197], s[6:7], v[0:1] op_sel_hi:[1,0,1]
	v_mov_b32_e32 v196, v174
	v_mov_b32_e32 v197, v198
	v_mov_b32_e32 v198, v175
	v_pk_add_f32 v[4:5], v[10:11], v[4:5]
	v_mov_b32_e32 v10, v18
	v_mov_b32_e32 v11, v6
	v_mov_b32_e32 v6, v19
	v_pk_fma_f32 v[28:29], v[202:203], s[6:7], v[2:3] op_sel_hi:[1,0,1]
	v_pk_mul_f32 v[0:1], v[30:31], v[30:31]
	v_pk_add_f32 v[196:197], v[196:197], v[198:199]
	v_mov_b32_e32 v198, v168
	v_mov_b32_e32 v199, v200
	v_mov_b32_e32 v200, v169
	v_pk_add_f32 v[6:7], v[10:11], v[6:7]
	v_pk_mul_f32 v[2:3], v[28:29], v[28:29]
	v_pk_add_f32 v[198:199], v[198:199], v[200:201]
	v_pk_add_f32 v[4:5], v[4:5], v[6:7]
	v_mov_b32_e32 v6, v30
	v_mov_b32_e32 v7, v0
	v_mov_b32_e32 v0, v31
	v_pk_add_f32 v[196:197], v[196:197], v[198:199]
	v_pk_add_f32 v[0:1], v[6:7], v[0:1]
	v_mov_b32_e32 v6, v28
	v_mov_b32_e32 v7, v2
	v_mov_b32_e32 v2, v29
	v_pk_add_f32 v[8:9], v[196:197], v[8:9]
	v_pk_add_f32 v[2:3], v[6:7], v[2:3]
	ds_bpermute_b32 v192, v181, v184
	ds_bpermute_b32 v193, v181, v185
	v_pk_add_f32 v[4:5], v[8:9], v[4:5]
	v_pk_add_f32 v[0:1], v[0:1], v[2:3]
	v_cndmask_b32_e32 v8, v183, v140, vcc
	v_pk_add_f32 v[0:1], v[4:5], v[0:1]
	ds_bpermute_b32 v2, v181, v0
	ds_bpermute_b32 v3, v181, v1
	s_waitcnt lgkmcnt(2)
	v_pk_add_f32 v[4:5], v[184:185], v[192:193]
	ds_bpermute_b32 v6, v180, v4
	ds_bpermute_b32 v7, v180, v5
	s_movk_i32 s6, 0x100
	s_waitcnt lgkmcnt(2)
	v_pk_add_f32 v[0:1], v[0:1], v[2:3]
	ds_bpermute_b32 v2, v180, v0
	ds_bpermute_b32 v3, v180, v1
	s_waitcnt lgkmcnt(2)
	v_pk_add_f32 v[4:5], v[4:5], v[6:7]
	ds_write_b64 v8, v[4:5]
	v_lshl_add_u32 v4, v191, 5, s7
	v_cndmask_b32_e32 v4, v183, v4, vcc
	s_waitcnt lgkmcnt(1)
	v_pk_add_f32 v[0:1], v[0:1], v[2:3]
	ds_write_b64 v4, v[0:1]
	v_or_b32_e32 v0, s19, v172
	v_cmp_gt_u32_e64 s[6:7], s6, v172
	v_ashrrev_i32_e32 v1, 31, v0
	s_waitcnt lgkmcnt(0)
	s_barrier
	s_and_saveexec_b64 s[24:25], s[6:7]
	s_cbranch_execz .LBB0_1050
	v_lshl_add_u32 v6, v172, 5, 0
	ds_read_b128 v[2:5], v6
	ds_read_b128 v[6:9], v6 offset:16
	s_ashr_i32 s21, s20, 31
	s_waitcnt lgkmcnt(1)
	v_add_f32_e32 v2, v2, v4
	v_add_f32_e32 v3, v3, v5
	v_lshlrev_b64 v[4:5], 5, v[0:1]
	s_waitcnt lgkmcnt(0)
	v_add_f32_e32 v2, v2, v6
	v_add_f32_e32 v3, v3, v7
	v_lshl_add_u64 v[4:5], s[22:23], 0, v[4:5]
	v_add_f32_e32 v2, v2, v8
	v_add_f32_e32 v3, v3, v9
	v_lshl_add_u64 v[4:5], s[20:21], 3, v[4:5]
	global_store_dwordx2 v[4:5], v[2:3], off sc1
.LBB0_1050:
	s_or_b64 exec, exec, s[24:25]
	s_waitcnt vmcnt(0)
	s_barrier
	s_mov_b64 s[20:21], exec
	v_readlane_b32 s24, v252, 6
	v_readlane_b32 s25, v252, 7
	s_and_b64 s[24:25], s[20:21], s[24:25]
	s_mov_b64 exec, s[24:25]
	s_cbranch_execz .LBB0_1067
	s_lshl_b32 s18, s18, 6
	s_ashr_i32 s19, s18, 31
	s_lshl_b64 s[18:19], s[18:19], 2
	s_mov_b64 s[24:25], exec
	s_add_u32 s9, s66, s18
	s_nop 0
	s_waitcnt vmcnt(0)
	s_waitcnt vmcnt(0)
	s_addc_u32 s19, s67, s19
	v_mbcnt_lo_u32_b32 v2, s24, 0
	s_add_u32 s18, s9, 0x38a04000
	v_mbcnt_hi_u32_b32 v2, s25, v2
	s_addc_u32 s19, s19, 0
	v_cmp_eq_u32_e32 vcc, 0, v2
	s_and_saveexec_b64 s[26:27], vcc
	s_cbranch_execz .LBB0_1053
	s_bcnt1_i32_b64 s9, s[24:25]
	v_mov_b32_e32 v2, 0
	v_mov_b32_e32 v3, s9
	global_atomic_add v2, v3, s[18:19]

; __device__ __forceinline__ unsigned xb_ld(unsigned* p)              { return __hip_atomic_load(p, __ATOMIC_RELAXED, __HIP_MEMORY_SCOPE_AGENT); }
; __device__ __forceinline__ unsigned xb_add(unsigned* p, unsigned v) { return __hip_atomic_fetch_add(p, v, __ATOMIC_RELAXED, __HIP_MEMORY_SCOPE_AGENT); }
; #define XB_SPIN(cond, bar) do { unsigned _sp = 0; while (cond) { __builtin_amdgcn_s_sleep(1); \
;     if ((++_sp & 255u) == 0u) { if (xb_ld(&(bar)[XB_TMO])) break; if (_sp > XB_SPIN_CAP) { atomicAdd(&(bar)[XB_TMO], 1u); break; } } } } while (0)
;     __device__ __forceinline__ void fused(f32x4 (&acc)[2][2][4][2], const Unit& u, int wr, int wc, int fr, int fq, PG8_LAS unsigned char* lds, int wid, int lane) const {
;     ...
;         if (tid == 0) {
;             __builtin_amdgcn_fence(__ATOMIC_RELEASE, "agent");
;             asm volatile("s_waitcnt vmcnt(0)" ::: "memory");
;             unsigned* c = cnt + u.pm * 64;
;             xb_add(c, 1u);
;             XB_SPIN(xb_ld(c) < 4u, bar);
;             __builtin_amdgcn_fence(__ATOMIC_ACQUIRE, "agent");
;             asm volatile("s_waitcnt vmcnt(0)" ::: "memory");
;         }
.LBB0_1066:
	s_waitcnt vmcnt(0)
	s_nop 0
	s_waitcnt vmcnt(0)

; #define PG8_LAS __attribute__((address_space(3)))
;     __device__ __forceinline__ void fused(f32x4 (&acc)[2][2][4][2], const Unit& u, int wr, int wc, int fr, int fq, PG8_LAS unsigned char* lds, int wid, int lane) const {
;     ...
; #pragma unroll
;         for (int ai = 0; ai < 2; ++ai)
; #pragma unroll
;             for (int m = 0; m < 4; ++m) {
;                 const int rl = ai * 128 + wr * 64 + m * 16 + fr;
;                 const size_t roff = (size_t)(u.pm * 256 + rl) * 1024 + u.pn * 256 + wc * 32 + fq * 8;
;                 float s1 = 0.f, s2 = 0.f;
; #pragma unroll
;                 for (int bj = 0; bj < 2; ++bj) {
;                     float x[8];
;                     if (RES_BF16) ld8f((const bfu*)res + roff + bj * 128, x);
;                     else ld8f32((const float*)res + roff + bj * 128, x);
; #pragma unroll
;                     for (int n = 0; n < 2; ++n) {
;                         f32x4 v = acc[ai][bj][m][n];
;                         v[0] += ALPHA * x[4 * n]; v[1] += ALPHA * x[4 * n + 1]; v[2] += ALPHA * x[4 * n + 2]; v[3] += ALPHA * x[4 * n + 3];
;                         acc[ai][bj][m][n] = v;
;                         s1 += (v[0] + v[1]) + (v[2] + v[3]); s2 += (v[0] * v[0] + v[1] * v[1]) + (v[2] * v[2] + v[3] * v[3]);
;                     }
;                 }
;                 s1 += __shfl_xor(s1, 16); s1 += __shfl_xor(s1, 32); s2 += __shfl_xor(s2, 16); s2 += __shfl_xor(s2, 32);
;                 {
;                     PG8_LAS float* pd = (fq == 0) ? P + (rl * 4 + wc) * 2 : (PG8_LAS float*)(lds + 12288) + tid * 2;
;                     pd[0] = s1; pd[1] = s2;
;                 }
;             }
.LBB0_1255:
	s_add_u32 s10, s66, 0x38b80000
	s_addc_u32 s11, s67, 0
	s_lshl_b32 s23, s43, 8
	v_add_u32_e32 v130, s23, v152
	s_lshl_b32 s8, s22, 8
	v_ashrrev_i32_e32 v131, 31, v130
	s_ashr_i32 s9, s8, 31
	v_lshlrev_b64 v[132:133], 11, v[130:131]
	v_lshl_add_u64 v[132:133], s[14:15], 0, v[132:133]
	s_lshl_b64 s[24:25], s[8:9], 1
	s_mov_b32 s21, 0
	v_lshl_add_u64 v[132:133], v[132:133], 0, s[24:25]
	s_lshl_b32 s20, s42, 6
	v_lshl_add_u64 v[132:133], v[132:133], 0, s[20:21]
	v_mov_b32_e32 v129, 0
	v_lshl_add_u64 v[132:133], v[132:133], 0, v[128:129]
	s_barrier
	global_load_dwordx4 v[134:137], v[132:133], off
	global_load_dwordx4 v[138:141], v[132:133], off offset:256
	s_mov_b64 s[98:99], 0x8000
	v_lshl_add_u64 v[250:251], v[132:133], 0, s[98:99]
	global_load_dwordx4 v[196:199], v[250:251], off
	global_load_dwordx4 v[200:203], v[250:251], off offset:256
	s_mov_b64 s[98:99], 0x10000
	v_lshl_add_u64 v[250:251], v[132:133], 0, s[98:99]
	global_load_dwordx4 v[204:207], v[250:251], off
	global_load_dwordx4 v[208:211], v[250:251], off offset:256
	s_mov_b64 s[98:99], 0x18000
	v_lshl_add_u64 v[250:251], v[132:133], 0, s[98:99]
	global_load_dwordx4 v[212:215], v[250:251], off
	global_load_dwordx4 v[216:219], v[250:251], off offset:256
	s_mov_b64 s[98:99], 0x40000
	v_lshl_add_u64 v[250:251], v[132:133], 0, s[98:99]
	global_load_dwordx4 v[220:223], v[250:251], off
	global_load_dwordx4 v[224:227], v[250:251], off offset:256
	s_mov_b64 s[98:99], 0x48000
	v_lshl_add_u64 v[250:251], v[132:133], 0, s[98:99]
	global_load_dwordx4 v[228:231], v[250:251], off
	global_load_dwordx4 v[232:235], v[250:251], off offset:256
	s_mov_b64 s[98:99], 0x50000
	v_lshl_add_u64 v[250:251], v[132:133], 0, s[98:99]
	global_load_dwordx4 v[236:239], v[250:251], off
	global_load_dwordx4 v[240:243], v[250:251], off offset:256
	v_mbcnt_lo_u32_b32 v132, -1, 0
	v_mbcnt_hi_u32_b32 v142, -1, v132
	v_and_b32_e32 v133, 64, v142
	v_or_b32_e32 v153, 16, v152
	v_xor_b32_e32 v143, 16, v142
	v_add_u32_e32 v145, 64, v133
	v_xor_b32_e32 v144, 32, v142
	v_add_u32_e32 v132, s23, v153
	v_cmp_lt_i32_e32 vcc, v143, v145
	v_ashrrev_i32_e32 v133, 31, v132
	s_mov_b32 s6, 0x3f9837f0
	v_cndmask_b32_e32 v146, v142, v143, vcc
	v_cmp_lt_i32_e32 vcc, v144, v145
	v_lshlrev_b32_e32 v151, 2, v146
	s_waitcnt vmcnt(0)
	v_lshlrev_b32_e32 v154, 16, v135
	v_cndmask_b32_e32 v144, v142, v144, vcc
	v_lshlrev_b64 v[142:143], 11, v[132:133]
	v_lshl_add_u64 v[142:143], s[14:15], 0, v[142:143]
	v_lshl_add_u64 v[142:143], v[142:143], 0, s[24:25]
	v_lshl_add_u64 v[142:143], v[142:143], 0, s[20:21]
	v_lshl_add_u64 v[146:147], v[142:143], 0, v[128:129]
	v_lshlrev_b32_e32 v149, 2, v144
	s_waitcnt vmcnt(0)
	v_mov_b64_e32 v[142:143], v[196:197]
	v_mov_b64_e32 v[144:145], v[198:199]
	v_mov_b64_e32 v[158:159], v[200:201]
	v_mov_b64_e32 v[160:161], v[202:203]
	v_lshlrev_b32_e32 v146, 16, v134
	v_and_b32_e32 v147, 0xffff0000, v134
	v_and_b32_e32 v155, 0xffff0000, v135
	v_lshlrev_b32_e32 v156, 16, v136
	v_and_b32_e32 v157, 0xffff0000, v136
	v_lshlrev_b32_e32 v136, 16, v137
	v_and_b32_e32 v137, 0xffff0000, v137
	v_lshlrev_b32_e32 v162, 16, v138
	v_and_b32_e32 v163, 0xffff0000, v138
	v_lshlrev_b32_e32 v138, 16, v139
	v_and_b32_e32 v139, 0xffff0000, v139
	v_lshlrev_b32_e32 v164, 16, v140
	v_and_b32_e32 v165, 0xffff0000, v140
	v_lshlrev_b32_e32 v140, 16, v141
	v_and_b32_e32 v141, 0xffff0000, v141
	v_pk_fma_f32 v[134:135], v[146:147], s[6:7], v[124:125] op_sel_hi:[1,0,1]
	v_pk_fma_f32 v[126:127], v[154:155], s[6:7], v[126:127] op_sel_hi:[1,0,1]
	v_pk_fma_f32 v[124:125], v[156:157], s[6:7], v[120:121] op_sel_hi:[1,0,1]
	v_pk_fma_f32 v[122:123], v[136:137], s[6:7], v[122:123] op_sel_hi:[1,0,1]
	v_pk_fma_f32 v[120:121], v[162:163], s[6:7], v[116:117] op_sel_hi:[1,0,1]
	v_pk_fma_f32 v[118:119], v[138:139], s[6:7], v[118:119] op_sel_hi:[1,0,1]
	v_pk_fma_f32 v[116:117], v[164:165], s[6:7], v[112:113] op_sel_hi:[1,0,1]
	v_pk_fma_f32 v[112:113], v[140:141], s[6:7], v[114:115] op_sel_hi:[1,0,1]
	v_pk_add_f32 v[114:115], v[134:135], v[134:135] op_sel:[0,1] op_sel_hi:[1,0]
	v_pk_add_f32 v[136:137], v[126:127], v[126:127] op_sel:[0,1] op_sel_hi:[1,0]
	v_pk_mul_f32 v[138:139], v[134:135], v[134:135]
	v_pk_mul_f32 v[140:141], v[126:127], v[126:127]
	v_pk_mul_f32 v[146:147], v[124:125], v[124:125]
	v_mul_f32_e32 v148, v122, v122
	v_mov_b32_e32 v166, v124
	v_mov_b32_e32 v168, v122
	v_pk_fma_f32 v[174:175], v[122:123], v[122:123], v[148:149] op_sel_hi:[1,1,0]
	v_mov_b32_e32 v167, v138
	v_mov_b32_e32 v138, v125
	v_mov_b32_e32 v169, v140
	v_mov_b32_e32 v140, v123
	v_mov_b32_e32 v115, v146
	v_mov_b32_e32 v137, v147
	v_pk_add_f32 v[138:139], v[166:167], v[138:139]
	v_pk_add_f32 v[140:141], v[168:169], v[140:141]
	v_pk_add_f32 v[114:115], v[114:115], v[136:137]
	v_mov_b32_e32 v174, v129
	v_pk_mul_f32 v[154:155], v[120:121], v[120:121]
	v_pk_mul_f32 v[156:157], v[118:119], v[118:119]
	v_pk_add_f32 v[138:139], v[138:139], v[140:141]
	v_pk_add_f32 v[114:115], v[114:115], v[174:175]
	v_mov_b32_e32 v170, v120
	v_mov_b32_e32 v171, v154
	v_mov_b32_e32 v154, v121
	v_pk_add_f32 v[114:115], v[138:139], v[114:115]
	v_mov_b32_e32 v138, v118
	v_mov_b32_e32 v139, v156
	v_mov_b32_e32 v156, v119
	v_pk_add_f32 v[136:137], v[170:171], v[154:155]
	v_pk_add_f32 v[138:139], v[138:139], v[156:157]
	v_pk_mul_f32 v[162:163], v[116:117], v[116:117]
	v_pk_mul_f32 v[164:165], v[112:113], v[112:113]
	v_pk_add_f32 v[136:137], v[136:137], v[138:139]
	v_mov_b32_e32 v138, v112
	v_pk_add_f32 v[114:115], v[114:115], v[136:137]
	v_mov_b32_e32 v136, v116
	v_mov_b32_e32 v137, v162
	v_mov_b32_e32 v162, v117
	v_mov_b32_e32 v139, v164
	v_mov_b32_e32 v164, v113
	v_pk_add_f32 v[136:137], v[136:137], v[162:163]
	v_pk_add_f32 v[138:139], v[138:139], v[164:165]
	v_or_b32_e32 v154, 32, v152
	v_pk_add_f32 v[136:137], v[136:137], v[138:139]
	s_lshl_b32 s7, s42, 3
	v_pk_add_f32 v[114:115], v[114:115], v[136:137]
	ds_bpermute_b32 v136, v151, v114
	ds_bpermute_b32 v137, v151, v115
	s_add_i32 s7, s7, 0
	v_lshl_add_u32 v148, v172, 3, 0
	v_add_u32_e32 v156, 0x3000, v148
	v_lshl_add_u32 v155, v152, 5, s7
	s_waitcnt lgkmcnt(0)
; #define PG8_LAS __attribute__((address_space(3)))
;     __device__ __forceinline__ void fused(f32x4 (&acc)[2][2][4][2], const Unit& u, int wr, int wc, int fr, int fq, PG8_LAS unsigned char* lds, int wid, int lane) const {
;     ...
; #pragma unroll
;         for (int ai = 0; ai < 2; ++ai)
; #pragma unroll
;             for (int m = 0; m < 4; ++m) {
;                 const int rl = ai * 128 + wr * 64 + m * 16 + fr;
;                 const size_t roff = (size_t)(u.pm * 256 + rl) * 1024 + u.pn * 256 + wc * 32 + fq * 8;
;                 float s1 = 0.f, s2 = 0.f;
; #pragma unroll
;                 for (int bj = 0; bj < 2; ++bj) {
;                     float x[8];
;                     if (RES_BF16) ld8f((const bfu*)res + roff + bj * 128, x);
;                     else ld8f32((const float*)res + roff + bj * 128, x);
; #pragma unroll
;                     for (int n = 0; n < 2; ++n) {
;                         f32x4 v = acc[ai][bj][m][n];
;                         v[0] += ALPHA * x[4 * n]; v[1] += ALPHA * x[4 * n + 1]; v[2] += ALPHA * x[4 * n + 2]; v[3] += ALPHA * x[4 * n + 3];
;                         acc[ai][bj][m][n] = v;
;                         s1 += (v[0] + v[1]) + (v[2] + v[3]); s2 += (v[0] * v[0] + v[1] * v[1]) + (v[2] * v[2] + v[3] * v[3]);
;                     }
;                 }
;                 s1 += __shfl_xor(s1, 16); s1 += __shfl_xor(s1, 32); s2 += __shfl_xor(s2, 16); s2 += __shfl_xor(s2, 32);
;                 {
;                     PG8_LAS float* pd = (fq == 0) ? P + (rl * 4 + wc) * 2 : (PG8_LAS float*)(lds + 12288) + tid * 2;
;                     pd[0] = s1; pd[1] = s2;
;                 }
;             }
	v_pk_add_f32 v[138:139], v[114:115], v[136:137]
	v_add_u32_e32 v136, s23, v154
	v_ashrrev_i32_e32 v137, 31, v136
	v_lshlrev_b64 v[140:141], 11, v[136:137]
	v_lshl_add_u64 v[140:141], s[14:15], 0, v[140:141]
	v_lshl_add_u64 v[140:141], v[140:141], 0, s[24:25]
	v_lshl_add_u64 v[140:141], v[140:141], 0, s[20:21]
	v_lshl_add_u64 v[140:141], v[140:141], 0, v[128:129]
	v_mov_b64_e32 v[162:163], v[204:205]
	v_mov_b64_e32 v[164:165], v[206:207]
	s_waitcnt vmcnt(2)
	v_lshlrev_b32_e32 v166, 16, v144
	v_and_b32_e32 v167, 0xffff0000, v144
	v_lshlrev_b32_e32 v144, 16, v145
	v_and_b32_e32 v145, 0xffff0000, v145
	v_lshlrev_b32_e32 v114, 16, v142
	v_and_b32_e32 v115, 0xffff0000, v142
	v_lshlrev_b32_e32 v142, 16, v143
	v_and_b32_e32 v143, 0xffff0000, v143
	v_pk_fma_f32 v[106:107], v[144:145], s[6:7], v[106:107] op_sel_hi:[1,0,1]
	v_pk_fma_f32 v[114:115], v[114:115], s[6:7], v[108:109] op_sel_hi:[1,0,1]
	v_pk_fma_f32 v[110:111], v[142:143], s[6:7], v[110:111] op_sel_hi:[1,0,1]
	v_pk_fma_f32 v[108:109], v[166:167], s[6:7], v[104:105] op_sel_hi:[1,0,1]
	v_mul_f32_e32 v104, v106, v106
	v_pk_add_f32 v[168:169], v[114:115], v[114:115] op_sel:[0,1] op_sel_hi:[1,0]
	v_pk_add_f32 v[170:171], v[110:111], v[110:111] op_sel:[0,1] op_sel_hi:[1,0]
	v_pk_mul_f32 v[144:145], v[108:109], v[108:109]
	v_pk_fma_f32 v[166:167], v[106:107], v[106:107], v[104:105] op_sel_hi:[1,1,0]
	s_waitcnt vmcnt(1)
	v_lshlrev_b32_e32 v104, 16, v158
	v_and_b32_e32 v105, 0xffff0000, v158
	v_pk_mul_f32 v[174:175], v[114:115], v[114:115]
	v_lshlrev_b32_e32 v158, 16, v159
	v_and_b32_e32 v159, 0xffff0000, v159
	v_lshlrev_b32_e32 v178, 16, v160
	v_and_b32_e32 v179, 0xffff0000, v160
	v_pk_fma_f32 v[100:101], v[104:105], s[6:7], v[100:101] op_sel_hi:[1,0,1]
	v_mov_b32_e32 v169, v144
	v_mov_b32_e32 v171, v145
	v_pk_mul_f32 v[176:177], v[110:111], v[110:111]
	v_pk_fma_f32 v[104:105], v[158:159], s[6:7], v[102:103] op_sel_hi:[1,0,1]
	v_pk_mul_f32 v[158:159], v[100:101], v[100:101]
	v_pk_fma_f32 v[102:103], v[178:179], s[6:7], v[96:97] op_sel_hi:[1,0,1]
	v_mov_b32_e32 v178, v108
	v_mov_b32_e32 v179, v174
	v_mov_b32_e32 v174, v109
	v_pk_add_f32 v[144:145], v[168:169], v[170:171]
	v_mov_b32_e32 v166, v129
	v_pk_mul_f32 v[180:181], v[104:105], v[104:105]
	v_pk_add_f32 v[174:175], v[178:179], v[174:175]
	v_mov_b32_e32 v178, v106
	v_mov_b32_e32 v179, v176
	v_mov_b32_e32 v176, v107
	v_pk_add_f32 v[144:145], v[144:145], v[166:167]
	v_mov_b32_e32 v166, v100
	v_mov_b32_e32 v167, v158
	v_mov_b32_e32 v158, v101
	v_pk_add_f32 v[176:177], v[178:179], v[176:177]
	v_pk_add_f32 v[158:159], v[166:167], v[158:159]
	v_mov_b32_e32 v166, v104
	v_mov_b32_e32 v167, v180
	v_mov_b32_e32 v180, v105
	v_lshlrev_b32_e32 v160, 16, v161
	v_and_b32_e32 v161, 0xffff0000, v161
	v_pk_add_f32 v[174:175], v[174:175], v[176:177]
	v_pk_add_f32 v[166:167], v[166:167], v[180:181]
	v_pk_fma_f32 v[96:97], v[160:161], s[6:7], v[98:99] op_sel_hi:[1,0,1]
	v_pk_mul_f32 v[98:99], v[102:103], v[102:103]
	v_pk_add_f32 v[144:145], v[174:175], v[144:145]
	v_pk_add_f32 v[158:159], v[158:159], v[166:167]
	v_pk_mul_f32 v[160:161], v[96:97], v[96:97]
	v_pk_add_f32 v[144:145], v[144:145], v[158:159]
	v_mov_b32_e32 v158, v102
	v_mov_b32_e32 v159, v98
	v_mov_b32_e32 v98, v103
	v_pk_add_f32 v[98:99], v[158:159], v[98:99]
	v_mov_b32_e32 v158, v96
	v_mov_b32_e32 v159, v160
	v_mov_b32_e32 v160, v97
	v_pk_add_f32 v[158:159], v[158:159], v[160:161]
	ds_bpermute_b32 v146, v149, v138
	ds_bpermute_b32 v147, v149, v139
	v_pk_add_f32 v[98:99], v[98:99], v[158:159]
	v_cmp_eq_u32_e32 vcc, 0, v150
	v_pk_add_f32 v[98:99], v[144:145], v[98:99]
	ds_bpermute_b32 v144, v151, v98
	ds_bpermute_b32 v145, v151, v99
	v_cndmask_b32_e32 v157, v156, v155, vcc
	v_or_b32_e32 v155, 48, v152
	s_waitcnt lgkmcnt(2)
	v_pk_add_f32 v[166:167], v[138:139], v[146:147]
	v_add_u32_e32 v138, s23, v155
	v_ashrrev_i32_e32 v139, 31, v138
	s_waitcnt lgkmcnt(0)
	v_pk_add_f32 v[168:169], v[98:99], v[144:145]
	v_lshlrev_b64 v[144:145], 11, v[138:139]
	v_lshl_add_u64 v[144:145], s[14:15], 0, v[144:145]
	v_lshl_add_u64 v[144:145], v[144:145], 0, s[24:25]
	v_lshl_add_u64 v[144:145], v[144:145], 0, s[20:21]
	v_lshl_add_u64 v[158:159], v[144:145], 0, v[128:129]
	v_mov_b64_e32 v[144:145], v[212:213]
	v_mov_b64_e32 v[146:147], v[214:215]
	s_waitcnt vmcnt(1)
	v_lshlrev_b32_e32 v160, 16, v163
	v_mov_b64_e32 v[140:141], v[208:209]
	v_mov_b64_e32 v[142:143], v[210:211]
	v_and_b32_e32 v161, 0xffff0000, v163
	v_pk_fma_f32 v[94:95], v[160:161], s[6:7], v[94:95] op_sel_hi:[1,0,1]
	v_mov_b64_e32 v[158:159], v[216:217]
	v_mov_b64_e32 v[160:161], v[218:219]
	v_lshlrev_b32_e32 v98, 16, v162
	v_and_b32_e32 v99, 0xffff0000, v162
	v_lshlrev_b32_e32 v162, 16, v164
	v_and_b32_e32 v163, 0xffff0000, v164
	v_lshlrev_b32_e32 v164, 16, v165
	v_and_b32_e32 v165, 0xffff0000, v165
	v_pk_fma_f32 v[90:91], v[164:165], s[6:7], v[90:91] op_sel_hi:[1,0,1]
	v_pk_fma_f32 v[98:99], v[98:99], s[6:7], v[92:93] op_sel_hi:[1,0,1]
	v_pk_fma_f32 v[92:93], v[162:163], s[6:7], v[88:89] op_sel_hi:[1,0,1]
	v_mul_f32_e32 v88, v90, v90
	v_pk_add_f32 v[174:175], v[98:99], v[98:99] op_sel:[0,1] op_sel_hi:[1,0]
	v_pk_add_f32 v[176:177], v[94:95], v[94:95] op_sel:[0,1] op_sel_hi:[1,0]
	v_pk_mul_f32 v[162:163], v[92:93], v[92:93]
	v_pk_fma_f32 v[164:165], v[90:91], v[90:91], v[88:89] op_sel_hi:[1,1,0]
	v_pk_mul_f32 v[178:179], v[98:99], v[98:99]
	v_mov_b32_e32 v175, v162
	v_mov_b32_e32 v177, v163
	v_pk_mul_f32 v[180:181], v[94:95], v[94:95]
	v_pk_add_f32 v[162:163], v[174:175], v[176:177]
	v_mov_b32_e32 v164, v129
	v_pk_add_f32 v[162:163], v[162:163], v[164:165]
	ds_write_b64 v157, v[166:167]
	v_add_u32_e32 v157, 0x80, v152
	ds_bpermute_b32 v170, v149, v168
	ds_bpermute_b32 v171, v149, v169
	s_waitcnt vmcnt(2)
; #define PG8_LAS __attribute__((address_space(3)))
;     __device__ __forceinline__ void fused(f32x4 (&acc)[2][2][4][2], const Unit& u, int wr, int wc, int fr, int fq, PG8_LAS unsigned char* lds, int wid, int lane) const {
;     ...
; #pragma unroll
;         for (int ai = 0; ai < 2; ++ai)
; #pragma unroll
;             for (int m = 0; m < 4; ++m) {
;                 const int rl = ai * 128 + wr * 64 + m * 16 + fr;
;                 const size_t roff = (size_t)(u.pm * 256 + rl) * 1024 + u.pn * 256 + wc * 32 + fq * 8;
;                 float s1 = 0.f, s2 = 0.f;
; #pragma unroll
;                 for (int bj = 0; bj < 2; ++bj) {
;                     float x[8];
;                     if (RES_BF16) ld8f((const bfu*)res + roff + bj * 128, x);
;                     else ld8f32((const float*)res + roff + bj * 128, x);
; #pragma unroll
;                     for (int n = 0; n < 2; ++n) {
;                         f32x4 v = acc[ai][bj][m][n];
;                         v[0] += ALPHA * x[4 * n]; v[1] += ALPHA * x[4 * n + 1]; v[2] += ALPHA * x[4 * n + 2]; v[3] += ALPHA * x[4 * n + 3];
;                         acc[ai][bj][m][n] = v;
;                         s1 += (v[0] + v[1]) + (v[2] + v[3]); s2 += (v[0] * v[0] + v[1] * v[1]) + (v[2] * v[2] + v[3] * v[3]);
;                     }
;                 }
;                 s1 += __shfl_xor(s1, 16); s1 += __shfl_xor(s1, 32); s2 += __shfl_xor(s2, 16); s2 += __shfl_xor(s2, 32);
;                 {
;                     PG8_LAS float* pd = (fq == 0) ? P + (rl * 4 + wc) * 2 : (PG8_LAS float*)(lds + 12288) + tid * 2;
;                     pd[0] = s1; pd[1] = s2;
;                 }
;             }
	v_lshlrev_b32_e32 v174, 16, v146
	v_and_b32_e32 v175, 0xffff0000, v146
	s_waitcnt vmcnt(1)
	v_lshlrev_b32_e32 v88, 16, v140
	v_and_b32_e32 v89, 0xffff0000, v140
	v_lshlrev_b32_e32 v140, 16, v141
	v_and_b32_e32 v141, 0xffff0000, v141
	v_lshlrev_b32_e32 v182, 16, v142
	v_and_b32_e32 v183, 0xffff0000, v142
	v_pk_fma_f32 v[84:85], v[88:89], s[6:7], v[84:85] op_sel_hi:[1,0,1]
	v_pk_fma_f32 v[88:89], v[140:141], s[6:7], v[86:87] op_sel_hi:[1,0,1]
	v_pk_mul_f32 v[140:141], v[84:85], v[84:85]
	v_pk_fma_f32 v[86:87], v[182:183], s[6:7], v[80:81] op_sel_hi:[1,0,1]
	v_mov_b32_e32 v182, v92
	v_mov_b32_e32 v183, v178
	v_mov_b32_e32 v178, v93
	v_pk_mul_f32 v[184:185], v[88:89], v[88:89]
	v_pk_add_f32 v[178:179], v[182:183], v[178:179]
	v_mov_b32_e32 v182, v90
	v_mov_b32_e32 v183, v180
	v_mov_b32_e32 v180, v91
	v_mov_b32_e32 v164, v84
	v_mov_b32_e32 v165, v140
	v_mov_b32_e32 v140, v85
	v_pk_add_f32 v[180:181], v[182:183], v[180:181]
	v_pk_add_f32 v[140:141], v[164:165], v[140:141]
	v_mov_b32_e32 v164, v88
	v_mov_b32_e32 v165, v184
	v_mov_b32_e32 v184, v89
	v_lshlrev_b32_e32 v142, 16, v143
	v_and_b32_e32 v143, 0xffff0000, v143
	v_pk_add_f32 v[178:179], v[178:179], v[180:181]
	v_pk_add_f32 v[164:165], v[164:165], v[184:185]
	v_pk_fma_f32 v[80:81], v[142:143], s[6:7], v[82:83] op_sel_hi:[1,0,1]
	v_pk_mul_f32 v[82:83], v[86:87], v[86:87]
	v_pk_add_f32 v[162:163], v[178:179], v[162:163]
	v_pk_add_f32 v[140:141], v[140:141], v[164:165]
	v_pk_mul_f32 v[142:143], v[80:81], v[80:81]
	v_pk_add_f32 v[140:141], v[162:163], v[140:141]
	v_mov_b32_e32 v162, v86
	v_mov_b32_e32 v163, v82
	v_mov_b32_e32 v82, v87
	v_pk_add_f32 v[82:83], v[162:163], v[82:83]
	v_mov_b32_e32 v162, v80
	v_mov_b32_e32 v163, v142
	v_mov_b32_e32 v142, v81
	v_pk_add_f32 v[142:143], v[162:163], v[142:143]
	v_lshlrev_b32_e32 v146, 16, v147
	v_pk_add_f32 v[82:83], v[82:83], v[142:143]
	v_and_b32_e32 v147, 0xffff0000, v147
	v_pk_add_f32 v[82:83], v[140:141], v[82:83]
	ds_bpermute_b32 v140, v151, v82
	ds_bpermute_b32 v141, v151, v83
	v_pk_fma_f32 v[74:75], v[146:147], s[6:7], v[74:75] op_sel_hi:[1,0,1]
	v_lshl_add_u32 v142, v153, 5, s7
	v_cndmask_b32_e32 v173, v156, v142, vcc
	s_waitcnt lgkmcnt(2)
	v_pk_add_f32 v[142:143], v[168:169], v[170:171]
	s_waitcnt lgkmcnt(0)
	v_pk_add_f32 v[166:167], v[82:83], v[140:141]
	v_add_u32_e32 v140, s23, v157
	v_ashrrev_i32_e32 v141, 31, v140
	v_lshlrev_b32_e32 v82, 16, v144
	v_lshlrev_b64 v[162:163], 11, v[140:141]
	v_and_b32_e32 v83, 0xffff0000, v144
	v_lshl_add_u64 v[162:163], s[14:15], 0, v[162:163]
	v_lshlrev_b32_e32 v144, 16, v145
	v_and_b32_e32 v145, 0xffff0000, v145
	v_pk_fma_f32 v[82:83], v[82:83], s[6:7], v[76:77] op_sel_hi:[1,0,1]
	v_pk_fma_f32 v[76:77], v[174:175], s[6:7], v[72:73] op_sel_hi:[1,0,1]
	v_mul_f32_e32 v72, v74, v74
	v_lshl_add_u64 v[162:163], v[162:163], 0, s[24:25]
	v_pk_fma_f32 v[78:79], v[144:145], s[6:7], v[78:79] op_sel_hi:[1,0,1]
	v_pk_fma_f32 v[184:185], v[74:75], v[74:75], v[72:73] op_sel_hi:[1,1,0]
	s_waitcnt vmcnt(0)
	v_lshlrev_b32_e32 v72, 16, v158
	v_and_b32_e32 v73, 0xffff0000, v158
	v_lshl_add_u64 v[162:163], v[162:163], 0, s[20:21]
	v_pk_add_f32 v[176:177], v[82:83], v[82:83] op_sel:[0,1] op_sel_hi:[1,0]
	v_pk_add_f32 v[178:179], v[78:79], v[78:79] op_sel:[0,1] op_sel_hi:[1,0]
	v_pk_mul_f32 v[174:175], v[76:77], v[76:77]
	v_lshlrev_b32_e32 v158, 16, v159
	v_and_b32_e32 v159, 0xffff0000, v159
	v_pk_fma_f32 v[68:69], v[72:73], s[6:7], v[68:69] op_sel_hi:[1,0,1]
	v_lshl_add_u64 v[170:171], v[162:163], 0, v[128:129]
	v_pk_fma_f32 v[72:73], v[158:159], s[6:7], v[70:71] op_sel_hi:[1,0,1]
	v_pk_mul_f32 v[158:159], v[68:69], v[68:69]
	v_mov_b32_e32 v177, v174
	v_mov_b32_e32 v179, v175
	v_mov_b64_e32 v[162:163], v[220:221]
	v_mov_b64_e32 v[164:165], v[222:223]
	v_mov_b64_e32 v[144:145], v[224:225]
	v_mov_b64_e32 v[146:147], v[226:227]
	v_pk_mul_f32 v[180:181], v[82:83], v[82:83]
	v_lshlrev_b32_e32 v186, 16, v160
	v_and_b32_e32 v187, 0xffff0000, v160
	v_pk_mul_f32 v[170:171], v[72:73], v[72:73]
	v_pk_add_f32 v[174:175], v[176:177], v[178:179]
	v_mov_b32_e32 v176, v68
	v_mov_b32_e32 v177, v158
	v_mov_b32_e32 v158, v69
	v_pk_mul_f32 v[182:183], v[78:79], v[78:79]
	v_lshlrev_b32_e32 v160, 16, v161
	v_and_b32_e32 v161, 0xffff0000, v161
	v_pk_fma_f32 v[70:71], v[186:187], s[6:7], v[64:65] op_sel_hi:[1,0,1]
	v_mov_b32_e32 v186, v76
	v_mov_b32_e32 v187, v180
	v_mov_b32_e32 v180, v77
	v_pk_add_f32 v[158:159], v[176:177], v[158:159]
	v_mov_b32_e32 v176, v72
	v_mov_b32_e32 v177, v170
	v_mov_b32_e32 v170, v73
	v_pk_fma_f32 v[64:65], v[160:161], s[6:7], v[66:67] op_sel_hi:[1,0,1]
	v_pk_mul_f32 v[66:67], v[70:71], v[70:71]
	v_pk_add_f32 v[180:181], v[186:187], v[180:181]
	v_mov_b32_e32 v186, v74
	v_mov_b32_e32 v187, v182
	v_mov_b32_e32 v182, v75
	v_pk_add_f32 v[170:171], v[176:177], v[170:171]
	v_pk_mul_f32 v[160:161], v[64:65], v[64:65]
	v_pk_add_f32 v[182:183], v[186:187], v[182:183]
	v_mov_b32_e32 v184, v129
	v_pk_add_f32 v[158:159], v[158:159], v[170:171]
	v_mov_b32_e32 v170, v70
	v_mov_b32_e32 v171, v66
	v_mov_b32_e32 v66, v71
	v_pk_add_f32 v[180:181], v[180:181], v[182:183]
	v_pk_add_f32 v[174:175], v[174:175], v[184:185]
	v_pk_add_f32 v[66:67], v[170:171], v[66:67]
	v_mov_b32_e32 v170, v64
	v_mov_b32_e32 v171, v160
	v_mov_b32_e32 v160, v65
	v_pk_add_f32 v[174:175], v[180:181], v[174:175]
	v_pk_add_f32 v[160:161], v[170:171], v[160:161]
	v_pk_add_f32 v[158:159], v[174:175], v[158:159]
	v_pk_add_f32 v[66:67], v[66:67], v[160:161]
	ds_write_b64 v173, v[142:143]
	v_pk_add_f32 v[66:67], v[158:159], v[66:67]
	ds_bpermute_b32 v158, v151, v66
	ds_bpermute_b32 v159, v151, v67
	v_lshl_add_u32 v142, v154, 5, s7
	v_cndmask_b32_e32 v173, v156, v142, vcc
	ds_bpermute_b32 v168, v149, v166
	ds_bpermute_b32 v169, v149, v167
	s_waitcnt lgkmcnt(2)
; #define PG8_LAS __attribute__((address_space(3)))
;     __device__ __forceinline__ void fused(f32x4 (&acc)[2][2][4][2], const Unit& u, int wr, int wc, int fr, int fq, PG8_LAS unsigned char* lds, int wid, int lane) const {
;     ...
; #pragma unroll
;         for (int ai = 0; ai < 2; ++ai)
; #pragma unroll
;             for (int m = 0; m < 4; ++m) {
;                 const int rl = ai * 128 + wr * 64 + m * 16 + fr;
;                 const size_t roff = (size_t)(u.pm * 256 + rl) * 1024 + u.pn * 256 + wc * 32 + fq * 8;
;                 float s1 = 0.f, s2 = 0.f;
; #pragma unroll
;                 for (int bj = 0; bj < 2; ++bj) {
;                     float x[8];
;                     if (RES_BF16) ld8f((const bfu*)res + roff + bj * 128, x);
;                     else ld8f32((const float*)res + roff + bj * 128, x);
; #pragma unroll
;                     for (int n = 0; n < 2; ++n) {
;                         f32x4 v = acc[ai][bj][m][n];
;                         v[0] += ALPHA * x[4 * n]; v[1] += ALPHA * x[4 * n + 1]; v[2] += ALPHA * x[4 * n + 2]; v[3] += ALPHA * x[4 * n + 3];
;                         acc[ai][bj][m][n] = v;
;                         s1 += (v[0] + v[1]) + (v[2] + v[3]); s2 += (v[0] * v[0] + v[1] * v[1]) + (v[2] * v[2] + v[3] * v[3]);
;                     }
;                 }
;                 s1 += __shfl_xor(s1, 16); s1 += __shfl_xor(s1, 32); s2 += __shfl_xor(s2, 16); s2 += __shfl_xor(s2, 32);
;                 {
;                     PG8_LAS float* pd = (fq == 0) ? P + (rl * 4 + wc) * 2 : (PG8_LAS float*)(lds + 12288) + tid * 2;
;                     pd[0] = s1; pd[1] = s2;
;                 }
;             }
	v_pk_add_f32 v[174:175], v[66:67], v[158:159]
	v_add_u32_e32 v158, 0x90, v152
	v_add_u32_e32 v142, s23, v158
	v_ashrrev_i32_e32 v143, 31, v142
	v_lshlrev_b64 v[160:161], 11, v[142:143]
	v_lshl_add_u64 v[160:161], s[14:15], 0, v[160:161]
	v_lshl_add_u64 v[160:161], v[160:161], 0, s[24:25]
	v_lshl_add_u64 v[160:161], v[160:161], 0, s[20:21]
	v_lshl_add_u64 v[160:161], v[160:161], 0, v[128:129]
	s_waitcnt lgkmcnt(0)
	v_pk_add_f32 v[170:171], v[166:167], v[168:169]
	v_mov_b64_e32 v[166:167], v[228:229]
	v_mov_b64_e32 v[168:169], v[230:231]
	ds_bpermute_b32 v176, v149, v174
	ds_bpermute_b32 v177, v149, v175
	ds_write_b64 v173, v[170:171]
	v_add_u32_e32 v159, 0xa0, v152
	s_waitcnt vmcnt(2)
	v_lshlrev_b32_e32 v178, 16, v164
	v_and_b32_e32 v179, 0xffff0000, v164
	v_lshlrev_b32_e32 v164, 16, v165
	v_and_b32_e32 v165, 0xffff0000, v165
	v_lshlrev_b32_e32 v66, 16, v162
	v_and_b32_e32 v67, 0xffff0000, v162
	v_lshlrev_b32_e32 v162, 16, v163
	v_and_b32_e32 v163, 0xffff0000, v163
	v_pk_fma_f32 v[58:59], v[164:165], s[6:7], v[58:59] op_sel_hi:[1,0,1]
	v_pk_fma_f32 v[66:67], v[66:67], s[6:7], v[60:61] op_sel_hi:[1,0,1]
	v_pk_fma_f32 v[62:63], v[162:163], s[6:7], v[62:63] op_sel_hi:[1,0,1]
	v_pk_fma_f32 v[60:61], v[178:179], s[6:7], v[56:57] op_sel_hi:[1,0,1]
	v_mul_f32_e32 v56, v58, v58
	v_mov_b64_e32 v[160:161], v[232:233]
	v_mov_b64_e32 v[162:163], v[234:235]
	v_pk_add_f32 v[180:181], v[66:67], v[66:67] op_sel:[0,1] op_sel_hi:[1,0]
	v_pk_add_f32 v[182:183], v[62:63], v[62:63] op_sel:[0,1] op_sel_hi:[1,0]
	v_pk_mul_f32 v[164:165], v[60:61], v[60:61]
	v_pk_fma_f32 v[178:179], v[58:59], v[58:59], v[56:57] op_sel_hi:[1,1,0]
	s_waitcnt vmcnt(2)
	v_lshlrev_b32_e32 v56, 16, v144
	v_and_b32_e32 v57, 0xffff0000, v144
	v_pk_mul_f32 v[184:185], v[66:67], v[66:67]
	v_lshlrev_b32_e32 v144, 16, v145
	v_and_b32_e32 v145, 0xffff0000, v145
	v_lshlrev_b32_e32 v188, 16, v146
	v_and_b32_e32 v189, 0xffff0000, v146
	v_pk_fma_f32 v[52:53], v[56:57], s[6:7], v[52:53] op_sel_hi:[1,0,1]
	v_mov_b32_e32 v181, v164
	v_mov_b32_e32 v183, v165
	v_pk_mul_f32 v[186:187], v[62:63], v[62:63]
	v_pk_fma_f32 v[56:57], v[144:145], s[6:7], v[54:55] op_sel_hi:[1,0,1]
	v_pk_mul_f32 v[144:145], v[52:53], v[52:53]
	v_pk_fma_f32 v[54:55], v[188:189], s[6:7], v[48:49] op_sel_hi:[1,0,1]
	v_mov_b32_e32 v188, v60
	v_mov_b32_e32 v189, v184
	v_mov_b32_e32 v184, v61
	v_pk_add_f32 v[164:165], v[180:181], v[182:183]
	v_mov_b32_e32 v178, v129
	v_pk_mul_f32 v[190:191], v[56:57], v[56:57]
	v_pk_add_f32 v[184:185], v[188:189], v[184:185]
	v_mov_b32_e32 v188, v58
	v_mov_b32_e32 v189, v186
	v_mov_b32_e32 v186, v59
	v_pk_add_f32 v[164:165], v[164:165], v[178:179]
	v_mov_b32_e32 v178, v52
	v_mov_b32_e32 v179, v144
	v_mov_b32_e32 v144, v53
	v_pk_add_f32 v[186:187], v[188:189], v[186:187]
	v_pk_add_f32 v[144:145], v[178:179], v[144:145]
	v_mov_b32_e32 v178, v56
	v_mov_b32_e32 v179, v190
	v_mov_b32_e32 v190, v57
	v_lshlrev_b32_e32 v146, 16, v147
	v_and_b32_e32 v147, 0xffff0000, v147
	v_pk_add_f32 v[184:185], v[184:185], v[186:187]
	v_pk_add_f32 v[178:179], v[178:179], v[190:191]
	v_pk_fma_f32 v[48:49], v[146:147], s[6:7], v[50:51] op_sel_hi:[1,0,1]
	v_pk_mul_f32 v[50:51], v[54:55], v[54:55]
	v_pk_add_f32 v[164:165], v[184:185], v[164:165]
	v_pk_add_f32 v[144:145], v[144:145], v[178:179]
	v_pk_mul_f32 v[146:147], v[48:49], v[48:49]
	v_pk_add_f32 v[144:145], v[164:165], v[144:145]
	v_mov_b32_e32 v164, v54
	v_mov_b32_e32 v165, v50
	v_mov_b32_e32 v50, v55
	v_pk_add_f32 v[50:51], v[164:165], v[50:51]
	v_mov_b32_e32 v164, v48
	v_mov_b32_e32 v165, v146
	v_mov_b32_e32 v146, v49
	v_pk_add_f32 v[146:147], v[164:165], v[146:147]
	s_waitcnt vmcnt(1)
	v_lshlrev_b32_e32 v164, 16, v168
	v_pk_add_f32 v[50:51], v[50:51], v[146:147]
	v_lshl_add_u32 v146, v155, 5, s7
	v_pk_add_f32 v[50:51], v[144:145], v[50:51]
	ds_bpermute_b32 v144, v151, v50
	ds_bpermute_b32 v145, v151, v51
	v_cndmask_b32_e32 v173, v156, v146, vcc
	s_waitcnt lgkmcnt(3)
	v_pk_add_f32 v[146:147], v[174:175], v[176:177]
	v_and_b32_e32 v165, 0xffff0000, v168
	v_lshlrev_b32_e32 v168, 16, v169
	s_waitcnt lgkmcnt(0)
	v_pk_add_f32 v[174:175], v[50:51], v[144:145]
	v_lshlrev_b32_e32 v144, 16, v167
	v_and_b32_e32 v145, 0xffff0000, v167
	v_pk_fma_f32 v[46:47], v[144:145], s[6:7], v[46:47] op_sel_hi:[1,0,1]
	v_add_u32_e32 v144, s23, v159
	v_lshlrev_b32_e32 v50, 16, v166
	v_and_b32_e32 v51, 0xffff0000, v166
	v_ashrrev_i32_e32 v145, 31, v144
	v_pk_fma_f32 v[50:51], v[50:51], s[6:7], v[44:45] op_sel_hi:[1,0,1]
	v_pk_fma_f32 v[44:45], v[164:165], s[6:7], v[40:41] op_sel_hi:[1,0,1]
	v_lshlrev_b64 v[40:41], 11, v[144:145]
	v_lshl_add_u64 v[40:41], s[14:15], 0, v[40:41]
	v_lshl_add_u64 v[40:41], v[40:41], 0, s[24:25]
	v_lshl_add_u64 v[40:41], v[40:41], 0, s[20:21]
	v_lshl_add_u64 v[170:171], v[40:41], 0, v[128:129]
	v_mov_b64_e32 v[164:165], v[236:237]
	v_mov_b64_e32 v[166:167], v[238:239]
	v_and_b32_e32 v169, 0xffff0000, v169
	v_pk_fma_f32 v[42:43], v[168:169], s[6:7], v[42:43] op_sel_hi:[1,0,1]
	v_pk_add_f32 v[178:179], v[50:51], v[50:51] op_sel:[0,1] op_sel_hi:[1,0]
	v_mul_f32_e32 v40, v42, v42
	v_pk_fma_f32 v[188:189], v[42:43], v[42:43], v[40:41] op_sel_hi:[1,1,0]
	s_waitcnt vmcnt(1)
; #define PG8_LAS __attribute__((address_space(3)))
;     __device__ __forceinline__ void fused(f32x4 (&acc)[2][2][4][2], const Unit& u, int wr, int wc, int fr, int fq, PG8_LAS unsigned char* lds, int wid, int lane) const {
;     ...
; #pragma unroll
;         for (int ai = 0; ai < 2; ++ai)
; #pragma unroll
;             for (int m = 0; m < 4; ++m) {
;                 const int rl = ai * 128 + wr * 64 + m * 16 + fr;
;                 const size_t roff = (size_t)(u.pm * 256 + rl) * 1024 + u.pn * 256 + wc * 32 + fq * 8;
;                 float s1 = 0.f, s2 = 0.f;
; #pragma unroll
;                 for (int bj = 0; bj < 2; ++bj) {
;                     float x[8];
;                     if (RES_BF16) ld8f((const bfu*)res + roff + bj * 128, x);
;                     else ld8f32((const float*)res + roff + bj * 128, x);
; #pragma unroll
;                     for (int n = 0; n < 2; ++n) {
;                         f32x4 v = acc[ai][bj][m][n];
;                         v[0] += ALPHA * x[4 * n]; v[1] += ALPHA * x[4 * n + 1]; v[2] += ALPHA * x[4 * n + 2]; v[3] += ALPHA * x[4 * n + 3];
;                         acc[ai][bj][m][n] = v;
;                         s1 += (v[0] + v[1]) + (v[2] + v[3]); s2 += (v[0] * v[0] + v[1] * v[1]) + (v[2] * v[2] + v[3] * v[3]);
;                     }
;                 }
;                 s1 += __shfl_xor(s1, 16); s1 += __shfl_xor(s1, 32); s2 += __shfl_xor(s2, 16); s2 += __shfl_xor(s2, 32);
;                 {
;                     PG8_LAS float* pd = (fq == 0) ? P + (rl * 4 + wc) * 2 : (PG8_LAS float*)(lds + 12288) + tid * 2;
;                     pd[0] = s1; pd[1] = s2;
;                 }
;             }
	v_lshlrev_b32_e32 v40, 16, v160
	v_and_b32_e32 v41, 0xffff0000, v160
	v_pk_add_f32 v[180:181], v[46:47], v[46:47] op_sel:[0,1] op_sel_hi:[1,0]
	v_pk_mul_f32 v[182:183], v[50:51], v[50:51]
	v_pk_mul_f32 v[186:187], v[44:45], v[44:45]
	v_lshlrev_b32_e32 v160, 16, v161
	v_and_b32_e32 v161, 0xffff0000, v161
	v_pk_fma_f32 v[40:41], v[40:41], s[6:7], v[36:37] op_sel_hi:[1,0,1]
	v_pk_mul_f32 v[184:185], v[46:47], v[46:47]
	v_pk_fma_f32 v[38:39], v[160:161], s[6:7], v[38:39] op_sel_hi:[1,0,1]
	v_pk_mul_f32 v[160:161], v[40:41], v[40:41]
	v_mov_b32_e32 v192, v44
	v_mov_b32_e32 v193, v182
	v_mov_b32_e32 v182, v45
	v_mov_b32_e32 v179, v186
	v_mov_b32_e32 v181, v187
	v_pk_mul_f32 v[190:191], v[38:39], v[38:39]
	v_pk_add_f32 v[182:183], v[192:193], v[182:183]
	v_mov_b32_e32 v192, v42
	v_mov_b32_e32 v193, v184
	v_mov_b32_e32 v184, v43
	v_pk_add_f32 v[178:179], v[178:179], v[180:181]
	v_mov_b32_e32 v180, v40
	v_mov_b32_e32 v181, v160
	v_mov_b32_e32 v160, v41
	v_lshlrev_b32_e32 v168, 16, v162
	v_and_b32_e32 v169, 0xffff0000, v162
	v_pk_add_f32 v[184:185], v[192:193], v[184:185]
	v_mov_b32_e32 v188, v129
	v_pk_add_f32 v[160:161], v[180:181], v[160:161]
	v_mov_b32_e32 v180, v38
	v_mov_b32_e32 v181, v190
	v_mov_b32_e32 v190, v39
	v_lshlrev_b32_e32 v162, 16, v163
	v_and_b32_e32 v163, 0xffff0000, v163
	v_pk_fma_f32 v[36:37], v[168:169], s[6:7], v[32:33] op_sel_hi:[1,0,1]
	v_pk_add_f32 v[182:183], v[182:183], v[184:185]
	v_pk_add_f32 v[178:179], v[178:179], v[188:189]
	v_pk_add_f32 v[180:181], v[180:181], v[190:191]
	v_pk_fma_f32 v[32:33], v[162:163], s[6:7], v[34:35] op_sel_hi:[1,0,1]
	v_pk_mul_f32 v[34:35], v[36:37], v[36:37]
	v_pk_add_f32 v[178:179], v[182:183], v[178:179]
	v_pk_add_f32 v[160:161], v[160:161], v[180:181]
	v_pk_mul_f32 v[162:163], v[32:33], v[32:33]
	v_pk_add_f32 v[160:161], v[178:179], v[160:161]
	v_mov_b32_e32 v178, v36
	v_mov_b32_e32 v179, v34
	v_mov_b32_e32 v34, v37
	v_pk_add_f32 v[34:35], v[178:179], v[34:35]
	v_mov_b32_e32 v178, v32
	v_mov_b32_e32 v179, v162
	v_mov_b32_e32 v162, v33
	v_pk_add_f32 v[162:163], v[178:179], v[162:163]
	ds_bpermute_b32 v176, v149, v174
	v_pk_add_f32 v[34:35], v[34:35], v[162:163]
	ds_bpermute_b32 v177, v149, v175
	v_pk_add_f32 v[34:35], v[160:161], v[34:35]
	ds_bpermute_b32 v160, v151, v34
	ds_bpermute_b32 v161, v151, v35
	v_mov_b64_e32 v[168:169], v[240:241]
	v_mov_b64_e32 v[170:171], v[242:243]
	ds_write_b64 v173, v[146:147]
	v_lshl_add_u32 v146, v157, 5, s7
	v_cndmask_b32_e32 v173, v156, v146, vcc
	s_waitcnt lgkmcnt(1)
	v_pk_add_f32 v[34:35], v[34:35], v[160:161]
	v_add_u32_e32 v160, 0xb0, v152
	v_add_u32_e32 v146, s23, v160
	v_ashrrev_i32_e32 v147, 31, v146
	v_pk_add_f32 v[162:163], v[174:175], v[176:177]
	ds_bpermute_b32 v178, v149, v34
	ds_bpermute_b32 v179, v149, v35
	v_lshlrev_b64 v[174:175], 11, v[146:147]
	v_lshl_add_u64 v[174:175], s[14:15], 0, v[174:175]
	v_lshl_add_u64 v[174:175], v[174:175], 0, s[24:25]
	v_lshl_add_u64 v[174:175], v[174:175], 0, s[20:21]
	v_lshl_add_u64 v[180:181], v[174:175], 0, v[128:129]
	v_lshl_add_u32 v128, v158, 5, s7
	v_cndmask_b32_e32 v128, v156, v128, vcc
	s_waitcnt lgkmcnt(0)
	v_pk_add_f32 v[34:35], v[34:35], v[178:179]
	global_load_dwordx4 v[174:177], v[180:181], off
	ds_write_b64 v173, v[162:163]
	ds_write_b64 v128, v[34:35]
	s_waitcnt vmcnt(2)
	v_lshlrev_b32_e32 v34, 16, v164
	v_and_b32_e32 v35, 0xffff0000, v164
	v_lshlrev_b32_e32 v162, 16, v165
	v_and_b32_e32 v163, 0xffff0000, v165
	v_pk_fma_f32 v[34:35], v[34:35], s[6:7], v[28:29] op_sel_hi:[1,0,1]
	v_pk_fma_f32 v[28:29], v[162:163], s[6:7], v[30:31] op_sel_hi:[1,0,1]
	global_load_dwordx4 v[162:165], v[180:181], off offset:256
	v_lshlrev_b32_e32 v178, 16, v166
	v_and_b32_e32 v179, 0xffff0000, v166
	v_lshlrev_b32_e32 v166, 16, v167
	v_and_b32_e32 v167, 0xffff0000, v167
	v_pk_fma_f32 v[26:27], v[166:167], s[6:7], v[26:27] op_sel_hi:[1,0,1]
	v_pk_fma_f32 v[30:31], v[178:179], s[6:7], v[24:25] op_sel_hi:[1,0,1]
	v_mul_f32_e32 v24, v26, v26
	v_pk_add_f32 v[182:183], v[34:35], v[34:35] op_sel:[0,1] op_sel_hi:[1,0]
	v_pk_add_f32 v[184:185], v[28:29], v[28:29] op_sel:[0,1] op_sel_hi:[1,0]
	v_pk_mul_f32 v[166:167], v[30:31], v[30:31]
	v_pk_fma_f32 v[178:179], v[26:27], v[26:27], v[24:25] op_sel_hi:[1,1,0]
	v_pk_mul_f32 v[186:187], v[34:35], v[34:35]
	v_mov_b32_e32 v183, v166
	v_mov_b32_e32 v185, v167
	v_pk_mul_f32 v[180:181], v[28:29], v[28:29]
	v_pk_add_f32 v[166:167], v[182:183], v[184:185]
	v_mov_b32_e32 v178, v129
	v_pk_add_f32 v[166:167], v[166:167], v[178:179]
	v_lshl_add_u32 v161, v159, 5, s7
	s_waitcnt vmcnt(2)
	v_lshlrev_b32_e32 v24, 16, v168
	v_and_b32_e32 v25, 0xffff0000, v168
	v_lshlrev_b32_e32 v168, 16, v169
	v_and_b32_e32 v169, 0xffff0000, v169
	v_lshlrev_b32_e32 v188, 16, v170
	v_and_b32_e32 v189, 0xffff0000, v170
	v_pk_fma_f32 v[24:25], v[24:25], s[6:7], v[20:21] op_sel_hi:[1,0,1]
	v_pk_fma_f32 v[22:23], v[168:169], s[6:7], v[22:23] op_sel_hi:[1,0,1]
	v_pk_mul_f32 v[168:169], v[24:25], v[24:25]
	v_pk_fma_f32 v[20:21], v[188:189], s[6:7], v[16:17] op_sel_hi:[1,0,1]
	v_mov_b32_e32 v188, v30
	v_mov_b32_e32 v189, v186
	v_mov_b32_e32 v186, v31
	v_pk_mul_f32 v[190:191], v[22:23], v[22:23]
	v_pk_add_f32 v[186:187], v[188:189], v[186:187]
	v_mov_b32_e32 v188, v26
	v_mov_b32_e32 v189, v180
	v_mov_b32_e32 v180, v27
	v_mov_b32_e32 v178, v24
	v_mov_b32_e32 v179, v168
	v_mov_b32_e32 v168, v25
	v_pk_add_f32 v[180:181], v[188:189], v[180:181]
	v_pk_add_f32 v[168:169], v[178:179], v[168:169]
	v_mov_b32_e32 v178, v22
	v_mov_b32_e32 v179, v190
	v_mov_b32_e32 v190, v23
	v_lshlrev_b32_e32 v170, 16, v171
	v_and_b32_e32 v171, 0xffff0000, v171
	v_pk_add_f32 v[180:181], v[186:187], v[180:181]
	v_pk_add_f32 v[178:179], v[178:179], v[190:191]
	v_pk_fma_f32 v[16:17], v[170:171], s[6:7], v[18:19] op_sel_hi:[1,0,1]
	v_pk_mul_f32 v[18:19], v[20:21], v[20:21]
	v_pk_add_f32 v[166:167], v[180:181], v[166:167]
	v_pk_add_f32 v[168:169], v[168:169], v[178:179]
	v_pk_mul_f32 v[170:171], v[16:17], v[16:17]
	v_pk_add_f32 v[166:167], v[166:167], v[168:169]
	v_mov_b32_e32 v168, v20
	v_mov_b32_e32 v169, v18
	v_mov_b32_e32 v18, v21
	v_pk_add_f32 v[18:19], v[168:169], v[18:19]
	v_mov_b32_e32 v168, v16
	v_mov_b32_e32 v169, v170
	v_mov_b32_e32 v170, v17
	v_pk_add_f32 v[168:169], v[168:169], v[170:171]
	s_waitcnt vmcnt(1)
; #define PG8_LAS __attribute__((address_space(3)))
; __device__ __forceinline__ unsigned xb_ld(unsigned* p)              { return __hip_atomic_load(p, __ATOMIC_RELAXED, __HIP_MEMORY_SCOPE_AGENT); }
; __device__ __forceinline__ unsigned xb_add(unsigned* p, unsigned v) { return __hip_atomic_fetch_add(p, v, __ATOMIC_RELAXED, __HIP_MEMORY_SCOPE_AGENT); }
; #define XB_SPIN(cond, bar) do { unsigned _sp = 0; while (cond) { __builtin_amdgcn_s_sleep(1); \
;     if ((++_sp & 255u) == 0u) { if (xb_ld(&(bar)[XB_TMO])) break; if (_sp > XB_SPIN_CAP) { atomicAdd(&(bar)[XB_TMO], 1u); break; } } } } while (0)
;     __device__ __forceinline__ void fused(f32x4 (&acc)[2][2][4][2], const Unit& u, int wr, int wc, int fr, int fq, PG8_LAS unsigned char* lds, int wid, int lane) const {
;     ...
;                 s1 += __shfl_xor(s1, 16); s1 += __shfl_xor(s1, 32); s2 += __shfl_xor(s2, 16); s2 += __shfl_xor(s2, 32);
;                 {
;                     PG8_LAS float* pd = (fq == 0) ? P + (rl * 4 + wc) * 2 : (PG8_LAS float*)(lds + 12288) + tid * 2;
;                     pd[0] = s1; pd[1] = s2;
;                 }
;             }
;         __syncthreads();
;         if (tid < 256) {
;             const float a = P[tid * 8] + P[tid * 8 + 2] + P[tid * 8 + 4] + P[tid * 8 + 6], b = P[tid * 8 + 1] + P[tid * 8 + 3] + P[tid * 8 + 5] + P[tid * 8 + 7];
;             const unsigned long long pk = (unsigned long long)__float_as_uint(a) | ((unsigned long long)__float_as_uint(b) << 32);
;             __hip_atomic_store(xch + ((size_t)(u.pm * 256 + tid) * 4 + u.pn), pk, __ATOMIC_RELAXED, __HIP_MEMORY_SCOPE_AGENT);
;         }
;         asm volatile("s_waitcnt vmcnt(0)" ::: "memory");
;         __syncthreads();
;         if (tid == 0) {
;             __builtin_amdgcn_fence(__ATOMIC_RELEASE, "agent");
;             asm volatile("s_waitcnt vmcnt(0)" ::: "memory");
;             unsigned* c = cnt + u.pm * 64;
;             xb_add(c, 1u);
;             XB_SPIN(xb_ld(c) < 4u, bar);
;             __builtin_amdgcn_fence(__ATOMIC_ACQUIRE, "agent");
;             asm volatile("s_waitcnt vmcnt(0)" ::: "memory");
;         }
	v_lshlrev_b32_e32 v170, 16, v175
	v_pk_add_f32 v[18:19], v[18:19], v[168:169]
	v_and_b32_e32 v171, 0xffff0000, v175
	v_pk_add_f32 v[166:167], v[166:167], v[18:19]
	v_lshlrev_b32_e32 v18, 16, v174
	v_and_b32_e32 v19, 0xffff0000, v174
	v_lshlrev_b32_e32 v174, 16, v176
	v_and_b32_e32 v175, 0xffff0000, v176
	v_lshlrev_b32_e32 v176, 16, v177
	v_and_b32_e32 v177, 0xffff0000, v177
	v_pk_fma_f32 v[18:19], v[18:19], s[6:7], v[12:13] op_sel_hi:[1,0,1]
	v_pk_fma_f32 v[12:13], v[170:171], s[6:7], v[14:15] op_sel_hi:[1,0,1]
	v_pk_fma_f32 v[14:15], v[174:175], s[6:7], v[8:9] op_sel_hi:[1,0,1]
	v_pk_fma_f32 v[8:9], v[176:177], s[6:7], v[10:11] op_sel_hi:[1,0,1]
	s_waitcnt vmcnt(0)
	v_lshlrev_b32_e32 v176, 16, v162
	v_and_b32_e32 v177, 0xffff0000, v162
	v_pk_mul_f32 v[180:181], v[18:19], v[18:19]
	v_mul_f32_e32 v128, v8, v8
	v_lshlrev_b32_e32 v162, 16, v163
	v_and_b32_e32 v163, 0xffff0000, v163
	v_pk_fma_f32 v[4:5], v[176:177], s[6:7], v[4:5] op_sel_hi:[1,0,1]
	v_pk_add_f32 v[170:171], v[18:19], v[18:19] op_sel:[0,1] op_sel_hi:[1,0]
	v_pk_add_f32 v[178:179], v[12:13], v[12:13] op_sel:[0,1] op_sel_hi:[1,0]
	v_pk_mul_f32 v[182:183], v[12:13], v[12:13]
	v_pk_mul_f32 v[10:11], v[14:15], v[14:15]
	v_pk_fma_f32 v[174:175], v[8:9], v[8:9], v[128:129] op_sel_hi:[1,1,0]
	v_pk_fma_f32 v[6:7], v[162:163], s[6:7], v[6:7] op_sel_hi:[1,0,1]
	v_pk_mul_f32 v[162:163], v[4:5], v[4:5]
	v_mov_b32_e32 v186, v14
	v_mov_b32_e32 v187, v180
	v_mov_b32_e32 v180, v15
	v_pk_mul_f32 v[176:177], v[6:7], v[6:7]
	v_pk_add_f32 v[180:181], v[186:187], v[180:181]
	v_mov_b32_e32 v186, v8
	v_mov_b32_e32 v187, v182
	v_mov_b32_e32 v182, v9
	v_mov_b32_e32 v171, v10
	v_mov_b32_e32 v179, v11
	v_mov_b32_e32 v174, v129
	v_mov_b32_e32 v128, v4
	v_mov_b32_e32 v129, v162
	v_mov_b32_e32 v162, v5
	v_lshlrev_b32_e32 v184, 16, v164
	v_and_b32_e32 v185, 0xffff0000, v164
	v_lshlrev_b32_e32 v164, 16, v165
	v_and_b32_e32 v165, 0xffff0000, v165
	v_pk_add_f32 v[182:183], v[186:187], v[182:183]
	v_pk_add_f32 v[10:11], v[170:171], v[178:179]
	v_pk_add_f32 v[128:129], v[128:129], v[162:163]
	v_mov_b32_e32 v162, v6
	v_mov_b32_e32 v163, v176
	v_mov_b32_e32 v176, v7
	v_pk_fma_f32 v[0:1], v[184:185], s[6:7], v[0:1] op_sel_hi:[1,0,1]
	v_pk_fma_f32 v[2:3], v[164:165], s[6:7], v[2:3] op_sel_hi:[1,0,1]
	v_pk_add_f32 v[180:181], v[180:181], v[182:183]
	v_pk_add_f32 v[10:11], v[10:11], v[174:175]
	v_pk_add_f32 v[162:163], v[162:163], v[176:177]
	v_pk_mul_f32 v[164:165], v[0:1], v[0:1]
	v_pk_mul_f32 v[184:185], v[2:3], v[2:3]
	v_pk_add_f32 v[10:11], v[180:181], v[10:11]
	v_pk_add_f32 v[128:129], v[128:129], v[162:163]
	v_mov_b32_e32 v162, v2
	v_pk_add_f32 v[10:11], v[10:11], v[128:129]
	v_mov_b32_e32 v128, v0
	v_mov_b32_e32 v129, v164
	v_mov_b32_e32 v164, v1
	v_mov_b32_e32 v163, v184
	v_mov_b32_e32 v184, v3
	v_pk_add_f32 v[128:129], v[128:129], v[164:165]
	v_pk_add_f32 v[162:163], v[162:163], v[184:185]
	ds_bpermute_b32 v168, v151, v166
	v_pk_add_f32 v[128:129], v[128:129], v[162:163]
	ds_bpermute_b32 v169, v151, v167
	v_pk_add_f32 v[10:11], v[10:11], v[128:129]
	ds_bpermute_b32 v128, v151, v10
	ds_bpermute_b32 v129, v151, v11
	v_cndmask_b32_e32 v151, v156, v161, vcc
	s_waitcnt lgkmcnt(2)
	v_pk_add_f32 v[162:163], v[166:167], v[168:169]
	ds_bpermute_b32 v164, v149, v162
	ds_bpermute_b32 v165, v149, v163
	s_waitcnt lgkmcnt(2)
	v_pk_add_f32 v[10:11], v[10:11], v[128:129]
	ds_bpermute_b32 v128, v149, v10
	ds_bpermute_b32 v129, v149, v11
	v_lshl_add_u32 v149, v160, 5, s7
	s_waitcnt lgkmcnt(2)
	v_pk_add_f32 v[162:163], v[162:163], v[164:165]
	v_cndmask_b32_e32 v149, v156, v149, vcc
	ds_write_b64 v151, v[162:163]
	s_waitcnt lgkmcnt(1)
	v_pk_add_f32 v[10:11], v[10:11], v[128:129]
	ds_write_b64 v149, v[10:11]
	s_movk_i32 s6, 0x100
	v_or_b32_e32 v10, s23, v172
	v_cmp_gt_u32_e64 s[6:7], s6, v172
	v_ashrrev_i32_e32 v11, 31, v10
	s_waitcnt lgkmcnt(0)
	s_barrier
	s_and_saveexec_b64 s[14:15], s[6:7]
	s_cbranch_execz .LBB0_1257
	v_lshl_add_u32 v128, v172, 5, 0
	ds_read_b128 v[162:165], v128
	ds_read_b128 v[166:169], v128 offset:16
	s_ashr_i32 s23, s22, 31
	s_waitcnt lgkmcnt(1)
	v_add_f32_e32 v128, v162, v164
	v_add_f32_e32 v129, v163, v165
	v_lshlrev_b64 v[162:163], 5, v[10:11]
	s_waitcnt lgkmcnt(0)
	v_add_f32_e32 v128, v128, v166
	v_add_f32_e32 v129, v129, v167
	v_lshl_add_u64 v[162:163], s[10:11], 0, v[162:163]
	v_add_f32_e32 v128, v128, v168
	v_add_f32_e32 v129, v129, v169
	v_lshl_add_u64 v[162:163], s[22:23], 3, v[162:163]
	global_store_dwordx2 v[162:163], v[128:129], off sc1
.LBB0_1257:
	s_or_b64 exec, exec, s[14:15]
	s_waitcnt vmcnt(0)
	s_barrier
	s_mov_b64 s[14:15], exec
	v_readlane_b32 s20, v252, 6
	v_readlane_b32 s21, v252, 7
	s_and_b64 s[20:21], s[14:15], s[20:21]
	s_mov_b64 exec, s[20:21]
	s_cbranch_execz .LBB0_1274
	s_lshl_b32 s20, s43, 6
	s_ashr_i32 s21, s20, 31
	s_lshl_b64 s[20:21], s[20:21], 2
	s_mov_b64 s[22:23], exec
	s_add_u32 s9, s66, s20
	s_nop 0
	s_waitcnt vmcnt(0)
	s_waitcnt vmcnt(0)
	s_addc_u32 s21, s67, s21
	v_mbcnt_lo_u32_b32 v128, s22, 0
	s_add_u32 s20, s9, 0x38a08000
	v_mbcnt_hi_u32_b32 v128, s23, v128
	s_addc_u32 s21, s21, 0
	v_cmp_eq_u32_e32 vcc, 0, v128
	s_and_saveexec_b64 s[24:25], vcc
	s_cbranch_execz .LBB0_1260
	s_bcnt1_i32_b64 s9, s[22:23]
	v_mov_b32_e32 v128, 0
	v_mov_b32_e32 v129, s9
	global_atomic_add v128, v129, s[20:21]
